# diff-attention loop: LDS address arithmetic hoisted (22 fewer VALU/iter), ones operand kept resident; plus XCD barrier at first seam and G3 layer-1 unit remap
# speedup vs baseline: 1.0253x; 1.0196x over previous
.LBB0_135:
	s_cmp_lt_i32 s90, 2
	s_cselect_b64 s[4:5], -1, 0
	s_cmp_gt_i32 s90, 1
	s_cselect_b64 s[0:1], -1, 0
	s_cmp_lt_i32 s91, 2
	s_cselect_b64 s[2:3], -1, 0
	s_or_b64 s[0:1], s[0:1], s[2:3]
	s_and_b64 vcc, exec, s[0:1]
	s_cbranch_vccnz .LBB0_212
	s_andn2_b64 vcc, exec, s[64:65]
	s_cbranch_vccnz .LBB0_204
	s_cmp_lg_u32 s90, 0
	s_waitcnt vmcnt(0)
	s_waitcnt lgkmcnt(0)
	s_barrier
	s_and_saveexec_b64 s[0:1], s[74:75]
	s_cbranch_execz .LBB0_191
	s_add_i32 s2, 0, 0x20000
	v_mov_b32_e32 v2, s2
	s_waitcnt vmcnt(0) expcnt(0) lgkmcnt(0)
	ds_read_b32 v4, v2
	s_add_i32 s2, 0, 0x20004
	v_mov_b32_e32 v2, s2
	ds_read_b32 v2, v2
	s_waitcnt lgkmcnt(1)
	v_cmp_ne_u32_e32 vcc, 0, v4
	s_cbranch_vccnz .LBB0_155
	s_add_u32 s6, s88, 0x10200
	s_addc_u32 s7, s89, 0
	s_add_u32 s8, s88, 0x10400
	s_addc_u32 s9, s89, 0
	s_add_u32 s10, s88, 0x10500
	s_addc_u32 s11, s89, 0
	s_add_u32 s12, s88, 0x10600
	s_addc_u32 s13, s89, 0
	s_add_u32 s14, s88, 0x10700
	s_addc_u32 s15, s89, 0
	s_add_u32 s16, s88, 0x10800
	s_addc_u32 s17, s89, 0
	s_add_u32 s18, s88, 0x10900
	s_addc_u32 s19, s89, 0
	s_add_u32 s20, s88, 0x10a00
	s_addc_u32 s21, s89, 0
	s_add_u32 s22, s88, 0x10b00
	s_addc_u32 s23, s89, 0
	s_add_u32 s24, s88, 0x10c00
	s_addc_u32 s25, s89, 0
	s_add_u32 s26, s88, 0x10d00
	s_addc_u32 s27, s89, 0
	s_add_u32 s28, s88, 0x10e00
	s_addc_u32 s29, s89, 0
	s_add_u32 s30, s88, 0x10f00
	s_addc_u32 s31, s89, 0
	s_add_u32 s34, s88, 0x11000
	s_addc_u32 s35, s89, 0
	s_add_u32 s36, s88, 0x11100
	s_addc_u32 s37, s89, 0
	s_add_u32 s38, s88, 0x11200
	v_readlane_b32 s2, v239, 0
	s_addc_u32 s39, s89, 0
	s_mul_i32 s2, s69, s2
	s_add_u32 s40, s88, 0x11300
	s_mul_i32 s2, s2, s68
	s_addc_u32 s41, s89, 0
	s_mov_b32 s3, 1
	v_mov_b32_e32 v18, 0
	s_branch .LBB0_142

.LBB0_924:
	s_ashr_i32 s2, s33, 8
	s_lshl_b32 s0, s33, 8
	s_lshl_b32 s35, s2, 14
	s_and_b32 s0, s0, 0x3f00
	v_mov_b32_e32 v50, v1
	s_or_b32 s0, s35, s0
	s_bfe_u32 s36, s33, 0x20006
	v_and_b32_e32 v3, 15, v50
	v_ashrrev_i32_e32 v2, 1, v50
	v_and_b32_e32 v2, 0xffffffe0, v2
	v_or_b32_e32 v4, s0, v3
	v_add_u32_e32 v140, v4, v2
	v_mad_i64_i32 v[4:5], s[0:1], v140, s21, v[134:135]
	s_lshl_b32 s12, s36, 7
	v_lshl_add_u64 v[4:5], v[4:5], 0, s[12:13]
	v_and_b32_e32 v136, 48, v50
	v_lshl_add_u64 v[4:5], v[4:5], 0, v[136:137]
	global_load_dwordx4 v[8:11], v[4:5], off offset:3136
	global_load_dwordx4 v[12:15], v[4:5], off offset:3200
	s_lshl_b32 s0, s2, 2
	s_lshl_b32 s1, s2, 3
	s_lshl_b32 s37, s36, 1
	s_or_b32 s2, s0, s36
	s_or_b32 s0, s37, s1
	s_ashr_i32 s1, s0, 31
	s_lshl_b32 s34, s36, 6
	s_lshl_b64 s[0:1], s[0:1], 2
	s_add_u32 s0, s88, s0
	s_addc_u32 s1, s89, s1
	global_load_dwordx2 v[4:5], v137, s[0:1]
	v_cmp_lt_i32_e32 vcc, v152, v153
	v_or_b32_e32 v142, 16, v140
	v_mad_i64_i32 v[16:17], s[0:1], v142, s21, v[134:135]
	v_cndmask_b32_e32 v2, v151, v152, vcc
	v_cmp_lt_i32_e32 vcc, v154, v153
	v_lshl_add_u64 v[16:17], v[16:17], 0, s[12:13]
	v_lshl_add_u64 v[20:21], v[16:17], 0, v[136:137]
	v_cndmask_b32_e32 v6, v151, v154, vcc
	v_lshlrev_b32_e32 v157, 2, v6
	v_lshlrev_b32_e32 v158, 2, v2
	global_load_dwordx4 v[16:19], v[20:21], off offset:3136
	s_mul_i32 s37, s2, 0x208000
	s_mul_hi_i32 s36, s2, 0x208000
	v_ashrrev_i32_e32 v161, 3, v50
	v_mov_b32_e32 v145, v137
	v_and_b32_e32 v159, 63, v50
	v_bfe_u32 v7, v50, 4, 2
	v_lshlrev_b32_e32 v66, 6, v161
	v_mul_lo_u32 v68, v161, s25
	v_lshlrev_b32_e32 v162, 6, v3
	v_mul_u32_u24_e32 v69, 0x48, v3
	v_ashrrev_i32_e32 v141, 31, v140
	v_ashrrev_i32_e32 v143, 31, v142
	v_lshlrev_b32_e32 v160, 2, v7
	v_lshlrev_b32_e32 v166, 1, v68
	v_lshlrev_b32_e32 v167, 1, v69
	v_mov_b32_e32 v68, v137
	v_mov_b32_e32 v69, v137
	v_mov_b32_e32 v70, 0
	v_mov_b32_e32 v71, v137
	v_mov_b32_e32 v72, v137
	v_mov_b32_e32 v73, v137
	v_mov_b32_e32 v74, 0
	v_mov_b32_e32 v75, v137
	v_mov_b32_e32 v76, v137
	v_mov_b32_e32 v77, v137
	v_mov_b32_e32 v78, 0
	v_mov_b32_e32 v79, v137
	v_mov_b32_e32 v80, v137
	v_mov_b32_e32 v81, v137
	v_mov_b32_e32 v90, 0
	v_mov_b32_e32 v91, v137
	v_mov_b32_e32 v92, v137
	v_mov_b32_e32 v93, v137
	v_mov_b32_e32 v94, 0
	v_mov_b32_e32 v95, v137
	v_mov_b32_e32 v96, v137
	v_mov_b32_e32 v97, v137
	v_mov_b32_e32 v98, 0
	v_mov_b32_e32 v99, v137
	v_mov_b32_e32 v100, v137
	v_mov_b32_e32 v101, v137
	v_mov_b32_e32 v102, 0
	v_mov_b32_e32 v103, v137
	v_mov_b32_e32 v104, v137
	v_mov_b32_e32 v105, v137
	v_mov_b32_e32 v106, 0
	v_mov_b32_e32 v107, v137
	v_mov_b32_e32 v108, v137
	v_mov_b32_e32 v109, v137
	v_mov_b32_e32 v110, 0
	v_mov_b32_e32 v111, v137
	v_mov_b32_e32 v112, v137
	v_mov_b32_e32 v113, v137
	v_mov_b32_e32 v118, 0
	v_mov_b32_e32 v119, v137
	s_waitcnt vmcnt(3)
	v_and_b32_e32 v23, 0xffff0000, v8
	v_lshlrev_b32_e32 v22, 16, v8
	v_and_b32_e32 v25, 0xffff0000, v9
	v_lshlrev_b32_e32 v24, 16, v9
	v_and_b32_e32 v9, 0xffff0000, v10
	v_lshlrev_b32_e32 v8, 16, v10
	v_and_b32_e32 v27, 0xffff0000, v11
	v_lshlrev_b32_e32 v26, 16, v11
	s_waitcnt vmcnt(2)
	v_and_b32_e32 v11, 0xffff0000, v12
	v_lshlrev_b32_e32 v10, 16, v12
	v_and_b32_e32 v29, 0xffff0000, v13
	v_lshlrev_b32_e32 v28, 16, v13
	v_pk_mul_f32 v[12:13], v[22:23], s[14:15] op_sel_hi:[1,0]
	v_pk_mul_f32 v[22:23], v[24:25], s[14:15] op_sel_hi:[1,0]
	v_and_b32_sdwa v6, v12, v155 dst_sel:DWORD dst_unused:UNUSED_PAD src0_sel:WORD_1 src1_sel:DWORD
	v_pk_mul_f32 v[8:9], v[8:9], s[14:15] op_sel_hi:[1,0]
	v_pk_mul_f32 v[24:25], v[26:27], s[14:15] op_sel_hi:[1,0]
	v_and_b32_sdwa v2, v13, v155 dst_sel:DWORD dst_unused:UNUSED_PAD src0_sel:WORD_1 src1_sel:DWORD
	v_and_b32_sdwa v26, v23, v155 dst_sel:DWORD dst_unused:UNUSED_PAD src0_sel:WORD_1 src1_sel:DWORD
	v_and_b32_sdwa v27, v22, v155 dst_sel:DWORD dst_unused:UNUSED_PAD src0_sel:WORD_1 src1_sel:DWORD
	v_add3_u32 v38, v12, v6, s22
	v_and_b32_sdwa v30, v9, v155 dst_sel:DWORD dst_unused:UNUSED_PAD src0_sel:WORD_1 src1_sel:DWORD
	v_and_b32_sdwa v31, v8, v155 dst_sel:DWORD dst_unused:UNUSED_PAD src0_sel:WORD_1 src1_sel:DWORD
	v_add3_u32 v34, v13, v2, s22
	v_add3_u32 v35, v23, v26, s22
	v_add3_u32 v39, v22, v27, s22
	v_and_b32_e32 v2, 0xffff0000, v38
	v_add3_u32 v36, v9, v30, s22
	v_add3_u32 v40, v8, v31, s22
	v_and_b32_e32 v6, 0xffff0000, v34
	v_and_b32_e32 v9, 0xffff0000, v35
	v_and_b32_e32 v8, 0xffff0000, v39
	v_mul_f32_e32 v2, v2, v2
	v_pk_mul_f32 v[8:9], v[8:9], v[8:9]
	v_fmac_f32_e32 v2, v6, v6
	v_and_b32_e32 v13, 0xffff0000, v36
	v_and_b32_e32 v12, 0xffff0000, v40
	v_add_f32_e32 v2, v8, v2
	v_pk_mul_f32 v[12:13], v[12:13], v[12:13]
	v_add_f32_e32 v2, v9, v2
	v_and_b32_sdwa v32, v25, v155 dst_sel:DWORD dst_unused:UNUSED_PAD src0_sel:WORD_1 src1_sel:DWORD
	v_and_b32_sdwa v33, v24, v155 dst_sel:DWORD dst_unused:UNUSED_PAD src0_sel:WORD_1 src1_sel:DWORD
	v_add_f32_e32 v2, v12, v2
	v_pk_mul_f32 v[8:9], v[10:11], s[14:15] op_sel_hi:[1,0]
	v_add3_u32 v37, v25, v32, s22
	v_add3_u32 v41, v24, v33, s22
	v_add_f32_e32 v2, v13, v2
	v_and_b32_sdwa v13, v8, v155 dst_sel:DWORD dst_unused:UNUSED_PAD src0_sel:WORD_1 src1_sel:DWORD
	v_and_b32_e32 v23, 0xffff0000, v37
	v_and_b32_e32 v22, 0xffff0000, v41
	v_add3_u32 v46, v8, v13, s22
	v_pk_mul_f32 v[22:23], v[22:23], v[22:23]
	v_pk_mul_f32 v[10:11], v[28:29], s[14:15] op_sel_hi:[1,0]
	v_and_b32_sdwa v12, v9, v155 dst_sel:DWORD dst_unused:UNUSED_PAD src0_sel:WORD_1 src1_sel:DWORD
	v_and_b32_e32 v8, 0xffff0000, v46
	v_add_f32_e32 v2, v22, v2
	v_and_b32_sdwa v22, v11, v155 dst_sel:DWORD dst_unused:UNUSED_PAD src0_sel:WORD_1 src1_sel:DWORD
	v_add3_u32 v42, v9, v12, s22
	v_mul_f32_e32 v12, v8, v8
	v_and_b32_sdwa v8, v10, v155 dst_sel:DWORD dst_unused:UNUSED_PAD src0_sel:WORD_1 src1_sel:DWORD
	v_and_b32_e32 v9, 0xffff0000, v42
	v_add3_u32 v43, v11, v22, s22
	v_add3_u32 v47, v10, v8, s22
	v_fmac_f32_e32 v12, v9, v9
	v_and_b32_e32 v9, 0xffff0000, v43
	v_and_b32_e32 v8, 0xffff0000, v47
	v_pk_mul_f32 v[8:9], v[8:9], v[8:9]
	v_add_f32_e32 v2, v23, v2
	v_add_f32_e32 v8, v8, v12
	v_add_f32_e32 v10, v9, v8
	v_and_b32_e32 v9, 0xffff0000, v14
	v_lshlrev_b32_e32 v8, 16, v14
	ds_bpermute_b32 v6, v158, v2
	v_pk_mul_f32 v[8:9], v[8:9], s[14:15] op_sel_hi:[1,0]
	v_perm_b32 v37, v37, v41, s26
	v_and_b32_sdwa v11, v9, v155 dst_sel:DWORD dst_unused:UNUSED_PAD src0_sel:WORD_1 src1_sel:DWORD
	v_and_b32_sdwa v12, v8, v155 dst_sel:DWORD dst_unused:UNUSED_PAD src0_sel:WORD_1 src1_sel:DWORD
	v_add3_u32 v44, v9, v11, s22
	v_add3_u32 v48, v8, v12, s22
	v_and_b32_e32 v9, 0xffff0000, v44
	v_and_b32_e32 v8, 0xffff0000, v48
	v_pk_mul_f32 v[8:9], v[8:9], v[8:9]
	s_waitcnt lgkmcnt(0)
	v_add_f32_e32 v2, v2, v6
	v_add_f32_e32 v8, v8, v10
	ds_bpermute_b32 v6, v157, v2
	v_add_f32_e32 v10, v9, v8
	v_and_b32_e32 v9, 0xffff0000, v15
	v_lshlrev_b32_e32 v8, 16, v15
	v_pk_mul_f32 v[8:9], v[8:9], s[14:15] op_sel_hi:[1,0]
	s_waitcnt lgkmcnt(0)
	v_add_f32_e32 v2, v2, v6
	v_and_b32_sdwa v11, v9, v155 dst_sel:DWORD dst_unused:UNUSED_PAD src0_sel:WORD_1 src1_sel:DWORD
	v_and_b32_sdwa v12, v8, v155 dst_sel:DWORD dst_unused:UNUSED_PAD src0_sel:WORD_1 src1_sel:DWORD
	v_add3_u32 v15, v9, v11, s22
	v_add3_u32 v45, v8, v12, s22
	v_and_b32_e32 v9, 0xffff0000, v15
	v_and_b32_e32 v8, 0xffff0000, v45
	v_pk_mul_f32 v[8:9], v[8:9], v[8:9]
	s_waitcnt vmcnt(1)
	v_mul_f32_e32 v2, v4, v2
	v_add_f32_e32 v8, v8, v10
	v_mul_f32_e32 v6, 0x4f800000, v2
	v_cmp_gt_f32_e32 vcc, s23, v2
	v_add_f32_e32 v8, v9, v8
	ds_bpermute_b32 v9, v158, v8
	v_cndmask_b32_e32 v2, v2, v6, vcc
	v_sqrt_f32_e32 v6, v2
	v_perm_b32 v36, v36, v40, s26
	v_perm_b32 v35, v35, v39, s26
	s_waitcnt lgkmcnt(0)
	v_add_f32_e32 v8, v8, v9
	v_add_u32_e32 v13, -1, v6
	v_fma_f32 v23, -v13, v6, v2
	ds_bpermute_b32 v9, v157, v8
	v_cmp_ge_f32_e64 s[0:1], 0, v23
	v_add_u32_e32 v11, 1, v6
	v_perm_b32 v34, v34, v38, s26
	v_cndmask_b32_e64 v10, v6, v13, s[0:1]
	v_fma_f32 v6, -v11, v6, v2
	v_cmp_lt_f32_e64 s[0:1], 0, v6
	s_waitcnt lgkmcnt(0)
	v_add_f32_e32 v8, v8, v9
	v_mul_f32_e32 v12, v5, v8
	v_cndmask_b32_e64 v6, v10, v11, s[0:1]
	v_mul_f32_e32 v10, 0x37800000, v6
	v_cndmask_b32_e32 v6, v6, v10, vcc
	global_load_dwordx4 v[8:11], v[20:21], off offset:3200
	v_mul_f32_e32 v13, 0x4f800000, v12
	v_cmp_gt_f32_e32 vcc, s23, v12
	v_cmp_class_f32_e64 s[0:1], v2, v139
	v_perm_b32 v45, v15, v45, s26
	v_cndmask_b32_e32 v14, v12, v13, vcc
	s_waitcnt vmcnt(1)
	v_and_b32_e32 v13, 0xffff0000, v16
	v_lshlrev_b32_e32 v12, 16, v16
	v_pk_mul_f32 v[12:13], v[12:13], s[14:15] op_sel_hi:[1,0]
	v_sqrt_f32_e32 v20, v14
	v_and_b32_sdwa v22, v12, v155 dst_sel:DWORD dst_unused:UNUSED_PAD src0_sel:WORD_1 src1_sel:DWORD
	v_and_b32_sdwa v16, v13, v155 dst_sel:DWORD dst_unused:UNUSED_PAD src0_sel:WORD_1 src1_sel:DWORD
	v_add3_u32 v49, v12, v22, s22
	v_add3_u32 v16, v13, v16, s22
	v_and_b32_e32 v12, 0xffff0000, v49
	v_mul_f32_e32 v22, v12, v12
	v_and_b32_e32 v12, 0xffff0000, v16
	v_fmac_f32_e32 v22, v12, v12
	v_and_b32_e32 v13, 0xffff0000, v17
	v_lshlrev_b32_e32 v12, 16, v17
	v_pk_mul_f32 v[12:13], v[12:13], s[14:15] op_sel_hi:[1,0]
	v_cndmask_b32_e64 v2, v6, v2, s[0:1]
	v_and_b32_sdwa v17, v13, v155 dst_sel:DWORD dst_unused:UNUSED_PAD src0_sel:WORD_1 src1_sel:DWORD
	v_and_b32_sdwa v23, v12, v155 dst_sel:DWORD dst_unused:UNUSED_PAD src0_sel:WORD_1 src1_sel:DWORD
	v_add3_u32 v17, v13, v17, s22
	v_add3_u32 v51, v12, v23, s22
	v_and_b32_e32 v13, 0xffff0000, v17
	v_and_b32_e32 v12, 0xffff0000, v51
	v_pk_mul_f32 v[12:13], v[12:13], v[12:13]
	v_add_u32_e32 v6, -1, v20
	v_add_f32_e32 v12, v12, v22
	v_add_f32_e32 v22, v13, v12
	v_and_b32_e32 v13, 0xffff0000, v18
	v_lshlrev_b32_e32 v12, 16, v18
	v_pk_mul_f32 v[12:13], v[12:13], s[14:15] op_sel_hi:[1,0]
	v_fma_f32 v21, -v6, v20, v14
	v_and_b32_sdwa v18, v13, v155 dst_sel:DWORD dst_unused:UNUSED_PAD src0_sel:WORD_1 src1_sel:DWORD
	v_and_b32_sdwa v23, v12, v155 dst_sel:DWORD dst_unused:UNUSED_PAD src0_sel:WORD_1 src1_sel:DWORD
	v_add3_u32 v54, v13, v18, s22
	v_add3_u32 v55, v12, v23, s22
	v_and_b32_e32 v13, 0xffff0000, v54
	v_and_b32_e32 v12, 0xffff0000, v55
	v_pk_mul_f32 v[12:13], v[12:13], v[12:13]
	v_cmp_ge_f32_e64 s[0:1], 0, v21
	v_add_f32_e32 v12, v12, v22
	v_add_f32_e32 v18, v13, v12
	v_and_b32_e32 v13, 0xffff0000, v19
	v_lshlrev_b32_e32 v12, 16, v19
	v_pk_mul_f32 v[12:13], v[12:13], s[14:15] op_sel_hi:[1,0]
	v_cndmask_b32_e64 v6, v20, v6, s[0:1]
	v_and_b32_sdwa v19, v13, v155 dst_sel:DWORD dst_unused:UNUSED_PAD src0_sel:WORD_1 src1_sel:DWORD
	v_and_b32_sdwa v22, v12, v155 dst_sel:DWORD dst_unused:UNUSED_PAD src0_sel:WORD_1 src1_sel:DWORD
	v_add3_u32 v56, v13, v19, s22
	v_add3_u32 v57, v12, v22, s22
	v_and_b32_e32 v13, 0xffff0000, v56
	v_and_b32_e32 v12, 0xffff0000, v57
	v_pk_mul_f32 v[12:13], v[12:13], v[12:13]
	v_xor_b32_e32 v2, 0x80000000, v2
	v_add_f32_e32 v12, v12, v18
	v_add_f32_e32 v12, v13, v12
	ds_bpermute_b32 v13, v158, v12
	v_add_u32_e32 v18, 1, v20
	v_fma_f32 v19, -v18, v20, v14
	v_cmp_lt_f32_e64 s[0:1], 0, v19
	v_perm_b32 v41, v56, v57, s26
	s_waitcnt lgkmcnt(0)
	v_add_f32_e32 v12, v12, v13
	ds_bpermute_b32 v13, v157, v12
	v_cndmask_b32_e64 v6, v6, v18, s[0:1]
	v_mul_f32_e32 v18, 0x37800000, v6
	v_cndmask_b32_e32 v6, v6, v18, vcc
	v_cmp_class_f32_e64 s[0:1], v14, v139
	s_waitcnt lgkmcnt(0)
	v_add_f32_e32 v12, v12, v13
	v_mul_f32_e32 v4, v4, v12
	v_mul_f32_e32 v12, 0x4f800000, v4
	v_cmp_gt_f32_e32 vcc, s23, v4
	v_cndmask_b32_e64 v6, v6, v14, s[0:1]
	v_xor_b32_e32 v6, 0x80000000, v6
	v_cndmask_b32_e32 v4, v4, v12, vcc
	v_sqrt_f32_e32 v18, v4
	v_perm_b32 v40, v54, v55, s26
	s_waitcnt vmcnt(0)
	v_and_b32_e32 v13, 0xffff0000, v8
	v_lshlrev_b32_e32 v12, 16, v8
	v_pk_mul_f32 v[12:13], v[12:13], s[14:15] op_sel_hi:[1,0]
	v_add_u32_e32 v14, -1, v18
	v_and_b32_sdwa v20, v12, v155 dst_sel:DWORD dst_unused:UNUSED_PAD src0_sel:WORD_1 src1_sel:DWORD
	v_and_b32_sdwa v8, v13, v155 dst_sel:DWORD dst_unused:UNUSED_PAD src0_sel:WORD_1 src1_sel:DWORD
	v_add3_u32 v59, v12, v20, s22
	v_add3_u32 v58, v13, v8, s22
	v_and_b32_e32 v8, 0xffff0000, v59
	v_mul_f32_e32 v20, v8, v8
	v_and_b32_e32 v8, 0xffff0000, v58
	v_and_b32_e32 v13, 0xffff0000, v9
	v_lshlrev_b32_e32 v12, 16, v9
	v_fmac_f32_e32 v20, v8, v8
	v_pk_mul_f32 v[8:9], v[12:13], s[14:15] op_sel_hi:[1,0]
	v_fma_f32 v19, -v14, v18, v4
	v_and_b32_sdwa v12, v9, v155 dst_sel:DWORD dst_unused:UNUSED_PAD src0_sel:WORD_1 src1_sel:DWORD
	v_and_b32_sdwa v13, v8, v155 dst_sel:DWORD dst_unused:UNUSED_PAD src0_sel:WORD_1 src1_sel:DWORD
	v_add3_u32 v60, v9, v12, s22
	v_add3_u32 v61, v8, v13, s22
	v_and_b32_e32 v9, 0xffff0000, v60
	v_and_b32_e32 v8, 0xffff0000, v61
	v_pk_mul_f32 v[8:9], v[8:9], v[8:9]
	v_cmp_ge_f32_e64 s[0:1], 0, v19
	v_add_f32_e32 v8, v8, v20
	v_add_f32_e32 v12, v9, v8
	v_and_b32_e32 v9, 0xffff0000, v10
	v_lshlrev_b32_e32 v8, 16, v10
	v_pk_mul_f32 v[8:9], v[8:9], s[14:15] op_sel_hi:[1,0]
	v_perm_b32 v39, v17, v51, s26
	v_and_b32_sdwa v10, v9, v155 dst_sel:DWORD dst_unused:UNUSED_PAD src0_sel:WORD_1 src1_sel:DWORD
	v_and_b32_sdwa v13, v8, v155 dst_sel:DWORD dst_unused:UNUSED_PAD src0_sel:WORD_1 src1_sel:DWORD
	v_add3_u32 v62, v9, v10, s22
	v_add3_u32 v63, v8, v13, s22
	v_and_b32_e32 v9, 0xffff0000, v62
	v_and_b32_e32 v8, 0xffff0000, v63
	v_pk_mul_f32 v[8:9], v[8:9], v[8:9]
	v_perm_b32 v38, v16, v49, s26
	v_add_f32_e32 v8, v8, v12
	v_add_f32_e32 v10, v9, v8
	v_and_b32_e32 v9, 0xffff0000, v11
	v_lshlrev_b32_e32 v8, 16, v11
	v_pk_mul_f32 v[8:9], v[8:9], s[14:15] op_sel_hi:[1,0]
	v_perm_b32 v44, v44, v48, s26
	v_and_b32_sdwa v11, v9, v155 dst_sel:DWORD dst_unused:UNUSED_PAD src0_sel:WORD_1 src1_sel:DWORD
	v_and_b32_sdwa v12, v8, v155 dst_sel:DWORD dst_unused:UNUSED_PAD src0_sel:WORD_1 src1_sel:DWORD
	v_add3_u32 v64, v9, v11, s22
	v_add3_u32 v65, v8, v12, s22
	v_and_b32_e32 v9, 0xffff0000, v64
	v_and_b32_e32 v8, 0xffff0000, v65
	v_pk_mul_f32 v[8:9], v[8:9], v[8:9]
	v_add_u32_e32 v11, 1, v18
	v_add_f32_e32 v8, v8, v10
	v_add_f32_e32 v8, v9, v8
	ds_bpermute_b32 v9, v158, v8
	v_fma_f32 v12, -v11, v18, v4
	v_cndmask_b32_e64 v10, v18, v14, s[0:1]
	v_cmp_lt_f32_e64 s[0:1], 0, v12
	v_perm_b32 v43, v43, v47, s26
	s_waitcnt lgkmcnt(0)
	v_add_f32_e32 v8, v8, v9
	ds_bpermute_b32 v9, v157, v8
	v_cndmask_b32_e64 v10, v10, v11, s[0:1]
	v_mul_f32_e32 v11, 0x37800000, v10
	v_cndmask_b32_e32 v10, v10, v11, vcc
	v_cmp_class_f32_e64 s[0:1], v4, v139
	s_waitcnt lgkmcnt(0)
	v_add_f32_e32 v8, v8, v9
	v_mul_f32_e32 v5, v5, v8
	v_mul_f32_e32 v8, 0x4f800000, v5
	v_cmp_gt_f32_e32 vcc, s23, v5
	v_cndmask_b32_e64 v4, v10, v4, s[0:1]
	v_xor_b32_e32 v10, 0x80000000, v4
	v_cndmask_b32_e32 v5, v5, v8, vcc
	v_sqrt_f32_e32 v8, v5
	v_mov_b32_e32 v12, v10
	v_mov_b32_e32 v13, v10
	v_perm_b32 v42, v42, v46, s26
	v_add_u32_e32 v4, -1, v8
	v_fma_f32 v9, -v4, v8, v5
	v_cmp_ge_f32_e64 s[0:1], 0, v9
	v_add_u32_e32 v9, 1, v8
	v_perm_b32 v49, v64, v65, s26
	v_cndmask_b32_e64 v4, v8, v4, s[0:1]
	v_fma_f32 v8, -v9, v8, v5
	v_cmp_lt_f32_e64 s[0:1], 0, v8
	v_perm_b32 v48, v62, v63, s26
	v_perm_b32 v47, v60, v61, s26
	v_cndmask_b32_e64 v4, v4, v9, s[0:1]
	v_mul_f32_e32 v8, 0x37800000, v4
	s_add_u32 s0, s3, s37
	v_cndmask_b32_e32 v4, v4, v8, vcc
	v_cmp_class_f32_e32 vcc, v5, v139
	s_addc_u32 s1, s15, s36
	s_and_b32 s38, s33, 0xffffff00
	v_cndmask_b32_e32 v4, v4, v5, vcc
	v_add_u32_e32 v11, s38, v161
	v_xor_b32_e32 v14, 0x80000000, v4
	v_add_u32_e32 v4, 0x8000, v11
	v_lshlrev_b32_e32 v8, 3, v50
	v_mad_i64_i32 v[4:5], s[36:37], v4, s21, v[134:135]
	v_and_b32_e32 v8, 56, v8
	v_lshl_add_u64 v[4:5], v[4:5], 0, s[12:13]
	v_lshlrev_b32_e32 v144, 1, v8
	v_mov_b64_e32 v[8:9], s[0:1]
	v_lshl_add_u64 v[4:5], v[4:5], 0, v[144:145]
	v_mad_i64_i32 v[8:9], s[0:1], v161, s24, v[8:9]
	v_lshl_add_u64 v[8:9], v[8:9], 0, v[144:145]
	global_load_dwordx4 v[18:21], v[4:5], off offset:3648
	global_load_dwordx4 v[22:25], v[8:9], off
	v_add_u32_e32 v4, 0x8040, v11
	v_mad_i64_i32 v[4:5], s[0:1], v4, s21, v[134:135]
	v_lshl_add_u64 v[4:5], v[4:5], 0, s[12:13]
	v_lshl_add_u64 v[4:5], v[4:5], 0, v[144:145]
	global_load_dwordx4 v[26:29], v[4:5], off offset:3648
	global_load_dwordx4 v[30:33], v[8:9], off offset:128
	v_mad_i64_i32 v[52:53], s[36:37], v161, s24, 0
	v_lshrrev_b32_e32 v4, 1, v161
	s_add_i32 s36, s38, 0x8080
	s_add_i32 s37, s38, 0x80c0
	v_xor_b32_e32 v4, v4, v50
	s_add_u32 s0, s8, s12
	v_lshlrev_b32_e32 v4, 3, v4
	s_addc_u32 s1, s9, 0
	v_and_b32_e32 v67, 56, v4
	v_bfe_u32 v4, v50, 1, 3
	v_lshl_add_u64 v[146:147], s[0:1], 0, v[144:145]
	v_mad_i64_i32 v[52:53], s[0:1], s2, v150, v[52:53]
	v_and_b32_e32 v50, 7, v50
	v_xor_b32_e32 v5, v7, v4
	v_bitop3_b32 v3, v7, v4, 4 bitop3:0x36
	v_lshl_or_b32 v52, v50, 4, v52
	v_lshlrev_b32_e32 v163, 3, v5
	v_lshlrev_b32_e32 v164, 3, v3
	v_mov_b32_e32 v3, v2
	v_mov_b32_e32 v4, v2
	v_mov_b32_e32 v5, v2
	v_mov_b32_e32 v11, v10
	v_mov_b32_e32 v7, v6
	v_mov_b32_e32 v8, v6
	v_mov_b32_e32 v9, v6
	v_mov_b32_e32 v15, v14
	v_mov_b32_e32 v16, v14
	v_mov_b32_e32 v17, v14
	v_perm_b32 v46, v58, v59, s26
	v_lshl_add_u64 v[148:149], s[10:11], 0, v[52:53]
	v_lshlrev_b32_e32 v145, 1, v66
	v_lshlrev_b32_e32 v165, 1, v67
	s_mov_b32 s12, 0
	s_mov_b32 s38, 0
	v_mov_b32_e32 v66, 0
	v_mov_b32_e32 v67, v137
	v_mov_b32_e32 v50, 0
	v_mov_b32_e32 v51, v137
	v_mov_b32_e32 v52, v137
	v_mov_b32_e32 v53, v137
	v_mov_b32_e32 v54, 0
	v_mov_b32_e32 v55, v137
	v_mov_b32_e32 v56, v137
	v_mov_b32_e32 v57, v137
	v_mov_b32_e32 v58, 0
	v_mov_b32_e32 v59, v137
	v_mov_b32_e32 v60, v137
	v_mov_b32_e32 v61, v137
	v_mov_b32_e32 v62, 0
	v_mov_b32_e32 v63, v137
	v_mov_b32_e32 v64, v137
	v_mov_b32_e32 v65, v137
	v_mov_b32_e32 v120, v137
	v_mov_b32_e32 v121, v137
	v_mov_b32_e32 v122, 0
	v_mov_b32_e32 v123, v137
	v_mov_b32_e32 v124, v137
	v_mov_b32_e32 v125, v137
	v_mov_b32_e32 v82, 0
	v_mov_b32_e32 v83, v137
	v_mov_b32_e32 v84, v137
	v_mov_b32_e32 v85, v137
	v_mov_b32_e32 v86, 0
	v_mov_b32_e32 v87, v137
	v_mov_b32_e32 v88, v137
	v_mov_b32_e32 v89, v137
	v_mov_b32_e32 v114, 0
	v_mov_b32_e32 v115, v137
	v_mov_b32_e32 v116, v137
	v_mov_b32_e32 v117, v137
	v_mov_b32_e32 v126, 0
	v_mov_b32_e32 v127, v137
	v_mov_b32_e32 v128, v137
	v_mov_b32_e32 v129, v137
	v_lshlrev_b32_e32 v246, 1, v162
	v_lshl_add_u32 v247, v164, 1, v246
	v_lshl_add_u32 v246, v163, 1, v246
	v_lshl_add_u32 v248, v160, 1, v167
	v_add_u32_e32 v244, v145, v165
	v_add_u32_e32 v245, v166, v144
	v_mov_b64_e32 v[240:241], s[4:5]
	v_mov_b64_e32 v[242:243], s[6:7]
	s_movk_i32 s99, 0x4800
	v_lshlrev_b32_e32 v136, 1, v160
	s_barrier
	s_branch .LBB0_926
.LBB0_925:
	ds_read_b128 v[130:133], v246
	ds_read_b128 v[168:171], v246 offset:2048
	s_waitcnt lgkmcnt(1)
	v_mfma_f32_16x16x32_bf16 v[172:175], v[130:133], v[34:37], v[2:5]
	ds_read_b128 v[184:187], v247 offset:2048
	v_mfma_f32_16x16x32_bf16 v[180:183], v[130:133], v[38:41], v[10:13]
	ds_read_b128 v[130:133], v247
	s_nop 2
	s_nop 1
	v_exp_f32_e32 v200, v172
	v_exp_f32_e32 v201, v175
	s_waitcnt lgkmcnt(2)
	v_mfma_f32_16x16x32_bf16 v[176:179], v[168:171], v[34:37], v[2:5]
	v_exp_f32_e32 v180, v180
	ds_read_b64 v[216:217], v248 offset:37376
	ds_read_b64 v[218:219], v248 offset:37408
	v_mfma_f32_16x16x32_bf16 v[168:171], v[168:171], v[38:41], v[10:13]
	ds_read_b64 v[220:221], v248 offset:39680
	ds_read_b64 v[222:223], v248 offset:39712
	s_nop 2
	v_exp_f32_e32 v204, v176
	v_exp_f32_e32 v176, v173
	s_waitcnt lgkmcnt(4)
	v_mfma_f32_16x16x32_bf16 v[188:191], v[130:133], v[42:45], v[6:9]
	v_exp_f32_e32 v205, v177
	v_exp_f32_e32 v213, v168
	v_exp_f32_e32 v168, v181
	v_mfma_f32_16x16x32_bf16 v[196:199], v[130:133], v[46:49], v[14:17]
	ds_read_b128 v[130:133], v246 offset:4096
	v_exp_f32_e32 v181, v169
	v_exp_f32_e32 v169, v182
	v_exp_f32_e32 v182, v170
	v_exp_f32_e32 v170, v183
	v_exp_f32_e32 v171, v171
	v_exp_f32_e32 v177, v174
	v_cvt_pk_bf16_f32 v168, v180, v168
	v_cvt_pk_bf16_f32 v169, v169, v170
	v_cvt_pk_bf16_f32 v170, v213, v181
	v_cvt_pk_bf16_f32 v171, v182, v171
	ds_read_b64 v[180:181], v248 offset:32768
	ds_read_b64 v[182:183], v248 offset:32800
	ds_read_b64 v[212:213], v248 offset:35072
	ds_read_b64 v[214:215], v248 offset:35104
	ds_read_b128 v[172:175], v246 offset:6144
	v_cvt_pk_bf16_f32 v176, v200, v176
	v_cvt_pk_bf16_f32 v177, v177, v201
	s_waitcnt lgkmcnt(5)
	v_mfma_f32_16x16x32_bf16 v[200:203], v[130:133], v[34:37], v[2:5]
	v_exp_f32_e32 v231, v190
	v_exp_f32_e32 v206, v178
	v_exp_f32_e32 v179, v179
	v_mfma_f32_16x16x32_bf16 v[208:211], v[130:133], v[38:41], v[10:13]
	v_exp_f32_e32 v188, v188
	v_mfma_f32_16x16x32_bf16 v[192:195], v[184:187], v[42:45], v[6:9]
	v_exp_f32_e32 v189, v189
	v_exp_f32_e32 v196, v196
	v_cvt_pk_bf16_f32 v178, v204, v205
	v_mfma_f32_16x16x32_bf16 v[184:187], v[184:187], v[46:49], v[14:17]
	v_cvt_pk_bf16_f32 v179, v206, v179
	s_nop 2
	v_exp_f32_e32 v192, v192
	v_exp_f32_e32 v193, v193
	v_mfma_f32_16x16x32_bf16 v[86:89], v[240:243], v[168:171], v[86:89]
	v_exp_f32_e32 v194, v194
	v_exp_f32_e32 v187, v187
	ds_read_b128 v[224:227], v247 offset:4096
	s_waitcnt lgkmcnt(4)
	v_mfma_f32_16x16x32_bf16 v[78:81], v[180:183], v[168:171], v[78:81]
	s_add_i32 s38, s38, 2
	s_addk_i32 s12, 0x80
	v_lshl_add_u64 v[148:149], v[148:149], 0, s[16:17]
	s_waitcnt lgkmcnt(2)
	v_mfma_f32_16x16x32_bf16 v[74:77], v[212:215], v[168:171], v[74:77]
	s_and_b64 vcc, exec, s[0:1]
	v_mfma_f32_16x16x32_bf16 v[70:73], v[216:219], v[168:171], v[70:73]
	v_mfma_f32_16x16x32_bf16 v[62:65], v[220:223], v[168:171], v[62:65]
	v_exp_f32_e32 v169, v191
	v_exp_f32_e32 v171, v195
	v_cvt_pk_bf16_f32 v168, v188, v189
	s_waitcnt lgkmcnt(1)
	v_mfma_f32_16x16x32_bf16 v[204:207], v[172:175], v[34:37], v[2:5]
	v_cvt_pk_bf16_f32 v169, v231, v169
	v_exp_f32_e32 v231, v184
	v_exp_f32_e32 v184, v197
	v_exp_f32_e32 v197, v185
	v_exp_f32_e32 v185, v198
	v_exp_f32_e32 v198, v186
	v_exp_f32_e32 v186, v199
	v_cvt_pk_bf16_f32 v170, v192, v193
	v_cvt_pk_bf16_f32 v171, v194, v171
	v_cvt_pk_bf16_f32 v184, v196, v184
	v_cvt_pk_bf16_f32 v185, v185, v186
	v_cvt_pk_bf16_f32 v186, v231, v197
	v_cvt_pk_bf16_f32 v187, v198, v187
	v_mfma_f32_16x16x32_bf16 v[172:175], v[172:175], v[38:41], v[10:13]
	v_exp_f32_e32 v196, v200
	v_exp_f32_e32 v197, v204
	v_exp_f32_e32 v198, v201
	v_mfma_f32_16x16x32_bf16 v[122:125], v[180:183], v[176:179], v[122:125]
	v_exp_f32_e32 v200, v207
	v_exp_f32_e32 v199, v203
	v_mfma_f32_16x16x32_bf16 v[102:105], v[180:183], v[168:171], v[102:105]
	v_mfma_f32_16x16x32_bf16 v[58:61], v[180:183], v[184:187], v[58:61]
	v_exp_f32_e32 v182, v205
	v_exp_f32_e32 v183, v206
	v_exp_f32_e32 v181, v202
	v_mfma_f32_16x16x32_bf16 v[126:129], v[240:243], v[176:179], v[126:129]
	v_cvt_pk_bf16_f32 v180, v196, v198
	v_cvt_pk_bf16_f32 v182, v197, v182
	v_cvt_pk_bf16_f32 v183, v183, v200
	v_mfma_f32_16x16x32_bf16 v[118:121], v[212:215], v[176:179], v[118:121]
	v_exp_f32_e32 v196, v208
	v_exp_f32_e32 v197, v172
	v_exp_f32_e32 v172, v209
	v_mfma_f32_16x16x32_bf16 v[110:113], v[216:219], v[176:179], v[110:113]
	v_exp_f32_e32 v200, v174
	v_cvt_pk_bf16_f32 v181, v181, v199
	v_exp_f32_e32 v198, v173
	v_mfma_f32_16x16x32_bf16 v[106:109], v[220:223], v[176:179], v[106:109]
	ds_read_b128 v[176:179], v247 offset:6144
	v_exp_f32_e32 v199, v210
	ds_read_b128 v[204:207], v246 offset:14336
	v_mfma_f32_16x16x32_bf16 v[114:117], v[240:243], v[168:171], v[114:117]
	v_mfma_f32_16x16x32_bf16 v[98:101], v[212:215], v[168:171], v[98:101]
	v_mfma_f32_16x16x32_bf16 v[94:97], v[216:219], v[168:171], v[94:97]
	v_mfma_f32_16x16x32_bf16 v[90:93], v[220:223], v[168:171], v[90:93]
	v_exp_f32_e32 v171, v175
	v_exp_f32_e32 v169, v211
	v_cvt_pk_bf16_f32 v168, v196, v172
	v_mfma_f32_16x16x32_bf16 v[82:85], v[240:243], v[184:187], v[82:85]
	v_cvt_pk_bf16_f32 v171, v200, v171
	v_mfma_f32_16x16x32_bf16 v[54:57], v[212:215], v[184:187], v[54:57]
	ds_read_b64 v[172:173], v248 offset:32832
	ds_read_b64 v[174:175], v248 offset:32864
	v_cvt_pk_bf16_f32 v169, v199, v169
	v_mfma_f32_16x16x32_bf16 v[50:53], v[216:219], v[184:187], v[50:53]
	v_cvt_pk_bf16_f32 v170, v197, v198
	ds_read_b64 v[196:197], v248 offset:37440
	ds_read_b64 v[198:199], v248 offset:37472
	ds_read_b64 v[200:201], v248 offset:39744
	ds_read_b64 v[202:203], v248 offset:39776
	v_mfma_f32_16x16x32_bf16 v[66:69], v[220:223], v[184:187], v[66:69]
	ds_read_b64 v[184:185], v248 offset:35136
	ds_read_b64 v[186:187], v248 offset:35168
	s_waitcnt lgkmcnt(10)
	v_mfma_f32_16x16x32_bf16 v[188:191], v[224:227], v[42:45], v[6:9]
	ds_read_b64 v[216:217], v248 offset:46592
	ds_read_b64 v[218:219], v248 offset:46624
	s_waitcnt lgkmcnt(11)
	v_mfma_f32_16x16x32_bf16 v[192:195], v[176:179], v[42:45], v[6:9]
	ds_read_b64 v[220:221], v248 offset:48896
	ds_read_b64 v[222:223], v248 offset:48928
	s_nop 1
	v_exp_f32_e32 v188, v188
	v_exp_f32_e32 v189, v189
	v_mfma_f32_16x16x32_bf16 v[224:227], v[224:227], v[46:49], v[14:17]
	v_exp_f32_e32 v190, v190
	s_nop 0
	v_exp_f32_e32 v192, v192
	v_exp_f32_e32 v193, v193
	v_mfma_f32_16x16x32_bf16 v[176:179], v[176:179], v[46:49], v[14:17]
	v_exp_f32_e32 v191, v191
	v_exp_f32_e32 v194, v194
	v_exp_f32_e32 v195, v195
	v_mfma_f32_16x16x32_bf16 v[126:129], v[240:243], v[180:183], v[126:129]
	v_cvt_pk_bf16_f32 v188, v188, v189
	v_cvt_pk_bf16_f32 v189, v190, v191
	v_cvt_pk_bf16_f32 v190, v192, v193
	v_mfma_f32_16x16x32_bf16 v[86:89], v[240:243], v[168:171], v[86:89]
	v_exp_f32_e32 v192, v224
	v_exp_f32_e32 v176, v176
	v_exp_f32_e32 v193, v225
	s_waitcnt lgkmcnt(10)
	v_mfma_f32_16x16x32_bf16 v[122:125], v[172:175], v[180:183], v[122:125]
	v_exp_f32_e32 v177, v177
	v_exp_f32_e32 v178, v178
	v_cvt_pk_bf16_f32 v191, v194, v195
	v_mfma_f32_16x16x32_bf16 v[78:81], v[172:175], v[168:171], v[78:81]
	s_waitcnt lgkmcnt(4)
	v_mfma_f32_16x16x32_bf16 v[118:121], v[184:187], v[180:183], v[118:121]
	v_mfma_f32_16x16x32_bf16 v[74:77], v[184:187], v[168:171], v[74:77]
	v_mfma_f32_16x16x32_bf16 v[110:113], v[196:199], v[180:183], v[110:113]
	v_mfma_f32_16x16x32_bf16 v[70:73], v[196:199], v[168:171], v[70:73]
	v_mfma_f32_16x16x32_bf16 v[106:109], v[200:203], v[180:183], v[106:109]
	v_exp_f32_e32 v180, v226
	v_mfma_f32_16x16x32_bf16 v[62:65], v[200:203], v[168:171], v[62:65]
	v_exp_f32_e32 v169, v227
	v_exp_f32_e32 v171, v179
	v_cvt_pk_bf16_f32 v168, v192, v193
	v_cvt_pk_bf16_f32 v170, v176, v177
	v_cvt_pk_bf16_f32 v169, v180, v169
	v_cvt_pk_bf16_f32 v171, v178, v171
	v_mfma_f32_16x16x32_bf16 v[102:105], v[172:175], v[188:191], v[102:105]
	ds_read_b128 v[224:227], v247 offset:12288
	v_mfma_f32_16x16x32_bf16 v[82:85], v[240:243], v[168:171], v[82:85]
	v_mfma_f32_16x16x32_bf16 v[58:61], v[172:175], v[168:171], v[58:61]
	ds_read_b128 v[172:175], v246 offset:8192
	v_mfma_f32_16x16x32_bf16 v[54:57], v[184:187], v[168:171], v[54:57]
	v_mfma_f32_16x16x32_bf16 v[50:53], v[196:199], v[168:171], v[50:53]
	v_mfma_f32_16x16x32_bf16 v[66:69], v[200:203], v[168:171], v[66:69]
	ds_read_b128 v[168:171], v246 offset:10240
	s_waitcnt lgkmcnt(1)
	v_mfma_f32_16x16x32_bf16 v[176:179], v[172:175], v[34:37], v[2:5]
	s_waitcnt lgkmcnt(0)
	v_mfma_f32_16x16x32_bf16 v[180:183], v[168:171], v[34:37], v[2:5]
	s_nop 5
	v_exp_f32_e32 v176, v176
	v_mfma_f32_16x16x32_bf16 v[172:175], v[172:175], v[38:41], v[10:13]
	v_exp_f32_e32 v208, v180
	v_exp_f32_e32 v177, v177
	v_exp_f32_e32 v209, v181
	v_mfma_f32_16x16x32_bf16 v[168:171], v[168:171], v[38:41], v[10:13]
	v_exp_f32_e32 v178, v178
	s_nop 2
	v_exp_f32_e32 v172, v172
	v_exp_f32_e32 v210, v182
	v_mfma_f32_16x16x32_bf16 v[114:117], v[240:243], v[188:191], v[114:117]
	v_exp_f32_e32 v179, v179
	v_exp_f32_e32 v213, v168
	v_exp_f32_e32 v168, v173
	v_exp_f32_e32 v173, v169
	v_exp_f32_e32 v169, v174
	v_exp_f32_e32 v174, v170
	v_exp_f32_e32 v170, v175
	v_exp_f32_e32 v171, v171
	v_mfma_f32_16x16x32_bf16 v[98:101], v[184:187], v[188:191], v[98:101]
	ds_read_b128 v[184:187], v247 offset:8192
	v_cvt_pk_bf16_f32 v168, v172, v168
	v_cvt_pk_bf16_f32 v169, v169, v170
	v_mfma_f32_16x16x32_bf16 v[94:97], v[196:199], v[188:191], v[94:97]
	v_cvt_pk_bf16_f32 v170, v213, v173
	v_cvt_pk_bf16_f32 v171, v174, v171
	ds_read_b64 v[172:173], v248 offset:41984
	ds_read_b64 v[174:175], v248 offset:42016
	v_mfma_f32_16x16x32_bf16 v[90:93], v[200:203], v[188:191], v[90:93]
	ds_read_b128 v[188:191], v247 offset:10240
	ds_read_b64 v[212:213], v248 offset:44288
	ds_read_b64 v[214:215], v248 offset:44320
	ds_read_b128 v[200:203], v246 offset:12288
	s_waitcnt lgkmcnt(6)
	v_mfma_f32_16x16x32_bf16 v[192:195], v[184:187], v[42:45], v[6:9]
	v_exp_f32_e32 v211, v183
	v_cvt_pk_bf16_f32 v176, v176, v177
	v_cvt_pk_bf16_f32 v177, v178, v179
	s_waitcnt lgkmcnt(3)
	v_mfma_f32_16x16x32_bf16 v[196:199], v[188:191], v[42:45], v[6:9]
	v_cvt_pk_bf16_f32 v178, v208, v209
	s_nop 1
	v_exp_f32_e32 v192, v192
	v_exp_f32_e32 v193, v193
	v_mfma_f32_16x16x32_bf16 v[184:187], v[184:187], v[46:49], v[14:17]
	s_nop 1
	v_exp_f32_e32 v196, v196
	v_exp_f32_e32 v197, v197
	v_exp_f32_e32 v228, v194
	v_mfma_f32_16x16x32_bf16 v[188:191], v[188:191], v[46:49], v[14:17]
	v_exp_f32_e32 v198, v198
	s_nop 0
	v_exp_f32_e32 v184, v184
	v_exp_f32_e32 v185, v185
	v_mfma_f32_16x16x32_bf16 v[86:89], v[240:243], v[168:171], v[86:89]
	v_exp_f32_e32 v186, v186
	s_nop 1
	v_exp_f32_e32 v188, v188
	v_exp_f32_e32 v189, v189
	v_mfma_f32_16x16x32_bf16 v[78:81], v[172:175], v[168:171], v[78:81]
	v_exp_f32_e32 v190, v190
	v_exp_f32_e32 v187, v187
	v_exp_f32_e32 v191, v191
	s_waitcnt lgkmcnt(1)
	v_mfma_f32_16x16x32_bf16 v[74:77], v[212:215], v[168:171], v[74:77]
	v_cvt_pk_bf16_f32 v179, v210, v211
	v_cvt_pk_bf16_f32 v184, v184, v185
	v_cvt_pk_bf16_f32 v185, v186, v187
	v_mfma_f32_16x16x32_bf16 v[70:73], v[216:219], v[168:171], v[70:73]
	v_cvt_pk_bf16_f32 v186, v188, v189
	v_cvt_pk_bf16_f32 v187, v190, v191
	v_mfma_f32_16x16x32_bf16 v[62:65], v[220:223], v[168:171], v[62:65]
	v_exp_f32_e32 v169, v195
	v_exp_f32_e32 v171, v199
	v_cvt_pk_bf16_f32 v168, v192, v193
	s_waitcnt lgkmcnt(0)
	v_mfma_f32_16x16x32_bf16 v[180:183], v[200:203], v[34:37], v[2:5]
	v_cvt_pk_bf16_f32 v169, v228, v169
	v_cvt_pk_bf16_f32 v170, v196, v197
	v_cvt_pk_bf16_f32 v171, v198, v171
	v_mfma_f32_16x16x32_bf16 v[208:211], v[204:207], v[34:37], v[2:5]
	v_mfma_f32_16x16x32_bf16 v[200:203], v[200:203], v[38:41], v[10:13]
	s_nop 2
	v_exp_f32_e32 v180, v180
	s_nop 2
	v_exp_f32_e32 v188, v208
	v_mfma_f32_16x16x32_bf16 v[204:207], v[204:207], v[38:41], v[10:13]
	v_mfma_f32_16x16x32_bf16 v[122:125], v[172:175], v[176:179], v[122:125]
	v_exp_f32_e32 v190, v202
	s_nop 5
	v_exp_f32_e32 v189, v205
	v_exp_f32_e32 v191, v207
	v_mfma_f32_16x16x32_bf16 v[102:105], v[172:175], v[168:171], v[102:105]
	v_mfma_f32_16x16x32_bf16 v[58:61], v[172:175], v[184:187], v[58:61]
	v_exp_f32_e32 v172, v181
	v_exp_f32_e32 v174, v209
	v_exp_f32_e32 v173, v182
	v_exp_f32_e32 v181, v183
	v_mfma_f32_16x16x32_bf16 v[126:129], v[240:243], v[176:179], v[126:129]
	v_exp_f32_e32 v175, v210
	v_exp_f32_e32 v182, v211
	v_cvt_pk_bf16_f32 v172, v180, v172
	v_mfma_f32_16x16x32_bf16 v[118:121], v[212:215], v[176:179], v[118:121]
	v_cvt_pk_bf16_f32 v173, v173, v181
	v_cvt_pk_bf16_f32 v174, v188, v174
	v_exp_f32_e32 v180, v200
	v_mfma_f32_16x16x32_bf16 v[110:113], v[216:219], v[176:179], v[110:113]
	v_exp_f32_e32 v188, v204
	v_exp_f32_e32 v181, v201
	v_cvt_pk_bf16_f32 v175, v175, v182
	v_mfma_f32_16x16x32_bf16 v[106:109], v[220:223], v[176:179], v[106:109]
	ds_read_b128 v[176:179], v247 offset:14336
	v_mfma_f32_16x16x32_bf16 v[114:117], v[240:243], v[168:171], v[114:117]
	v_mfma_f32_16x16x32_bf16 v[98:101], v[212:215], v[168:171], v[98:101]
	v_mfma_f32_16x16x32_bf16 v[94:97], v[216:219], v[168:171], v[94:97]
	v_mfma_f32_16x16x32_bf16 v[90:93], v[220:223], v[168:171], v[90:93]
	v_exp_f32_e32 v171, v206
	v_exp_f32_e32 v169, v203
	v_mfma_f32_16x16x32_bf16 v[82:85], v[240:243], v[184:187], v[82:85]
	v_cvt_pk_bf16_f32 v168, v180, v181
	ds_read_b64 v[180:181], v248 offset:42048
	ds_read_b64 v[182:183], v248 offset:42080
	v_cvt_pk_bf16_f32 v170, v188, v189
	v_mfma_f32_16x16x32_bf16 v[54:57], v[212:215], v[184:187], v[54:57]
	v_cvt_pk_bf16_f32 v169, v190, v169
	v_cvt_pk_bf16_f32 v171, v171, v191
	v_mfma_f32_16x16x32_bf16 v[50:53], v[216:219], v[184:187], v[50:53]
	ds_read_b64 v[188:189], v248 offset:46656
	ds_read_b64 v[190:191], v248 offset:46688
	ds_read_b64 v[200:201], v248 offset:48960
	ds_read_b64 v[202:203], v248 offset:48992
	v_mfma_f32_16x16x32_bf16 v[66:69], v[220:223], v[184:187], v[66:69]
	ds_read_b64 v[184:185], v248 offset:44352
	ds_read_b64 v[186:187], v248 offset:44384
	v_mfma_f32_16x16x32_bf16 v[192:195], v[224:227], v[42:45], v[6:9]
	s_waitcnt lgkmcnt(8)
	v_mfma_f32_16x16x32_bf16 v[196:199], v[176:179], v[42:45], v[6:9]
	v_mfma_f32_16x16x32_bf16 v[224:227], v[224:227], v[46:49], v[14:17]
	s_nop 4
	v_exp_f32_e32 v192, v192
	s_nop 0
	v_exp_f32_e32 v196, v196
	v_exp_f32_e32 v193, v193
	v_mfma_f32_16x16x32_bf16 v[176:179], v[176:179], v[46:49], v[14:17]
	v_exp_f32_e32 v197, v197
	v_exp_f32_e32 v194, v194
	v_exp_f32_e32 v195, v195
	v_mfma_f32_16x16x32_bf16 v[126:129], v[240:243], v[172:175], v[126:129]
	v_exp_f32_e32 v198, v198
	v_exp_f32_e32 v199, v199
	v_cvt_pk_bf16_f32 v192, v192, v193
	v_mfma_f32_16x16x32_bf16 v[86:89], v[240:243], v[168:171], v[86:89]
	v_cvt_pk_bf16_f32 v193, v194, v195
	v_cvt_pk_bf16_f32 v194, v196, v197
	v_exp_f32_e32 v196, v224
	s_waitcnt lgkmcnt(6)
	v_mfma_f32_16x16x32_bf16 v[122:125], v[180:183], v[172:175], v[122:125]
	v_exp_f32_e32 v176, v176
	v_exp_f32_e32 v197, v225
	v_cvt_pk_bf16_f32 v195, v198, v199
	v_mfma_f32_16x16x32_bf16 v[78:81], v[180:183], v[168:171], v[78:81]
	s_waitcnt lgkmcnt(0)
	v_mfma_f32_16x16x32_bf16 v[118:121], v[184:187], v[172:175], v[118:121]
	v_mfma_f32_16x16x32_bf16 v[74:77], v[184:187], v[168:171], v[74:77]
	v_mfma_f32_16x16x32_bf16 v[110:113], v[188:191], v[172:175], v[110:113]
	v_mfma_f32_16x16x32_bf16 v[70:73], v[188:191], v[168:171], v[70:73]
	v_mfma_f32_16x16x32_bf16 v[106:109], v[200:203], v[172:175], v[106:109]
	v_exp_f32_e32 v172, v177
	v_exp_f32_e32 v173, v226
	v_exp_f32_e32 v174, v178
	v_mfma_f32_16x16x32_bf16 v[62:65], v[200:203], v[168:171], v[62:65]
	v_exp_f32_e32 v169, v227
	v_exp_f32_e32 v171, v179
	v_cvt_pk_bf16_f32 v168, v196, v197
	v_cvt_pk_bf16_f32 v170, v176, v172
	v_cvt_pk_bf16_f32 v169, v173, v169
	v_cvt_pk_bf16_f32 v171, v174, v171
	v_mfma_f32_16x16x32_bf16 v[114:117], v[240:243], v[192:195], v[114:117]
	s_nop 0
	v_mfma_f32_16x16x32_bf16 v[82:85], v[240:243], v[168:171], v[82:85]
	v_mfma_f32_16x16x32_bf16 v[102:105], v[180:183], v[192:195], v[102:105]
	v_mfma_f32_16x16x32_bf16 v[58:61], v[180:183], v[168:171], v[58:61]
	v_mfma_f32_16x16x32_bf16 v[98:101], v[184:187], v[192:195], v[98:101]
	v_mfma_f32_16x16x32_bf16 v[54:57], v[184:187], v[168:171], v[54:57]
	v_mfma_f32_16x16x32_bf16 v[94:97], v[188:191], v[192:195], v[94:97]
	v_mfma_f32_16x16x32_bf16 v[50:53], v[188:191], v[168:171], v[50:53]
	v_mfma_f32_16x16x32_bf16 v[90:93], v[200:203], v[192:195], v[90:93]
	v_mfma_f32_16x16x32_bf16 v[66:69], v[200:203], v[168:171], v[66:69]
	v_xor_b32_e32 v246, 0x4000, v246
	v_xor_b32_e32 v247, 0x4000, v247
	v_xor_b32_e32 v244, 0x4000, v244
	v_add_u32_e32 v248, s99, v248
	v_add_u32_e32 v245, s99, v245
	s_sub_i32 s99, 0, s99
	s_cbranch_vccnz .LBB0_928
.LBB0_926:
	s_and_b32 s0, s12, 0x80
	s_lshl_b32 s1, s0, 7
	s_add_i32 s39, s1, 0
	s_lshl_b32 s0, s0, 4
	s_add_i32 s2, s39, s0
	s_cmpk_gt_u32 s38, 0x101
	s_cselect_b64 s[0:1], -1, 0
	s_and_b64 vcc, exec, s[0:1]
	s_waitcnt vmcnt(3)
	ds_write_b128 v244, v[18:21]
	s_waitcnt vmcnt(1)
	ds_write_b128 v245, v[22:25] offset:32768
	s_waitcnt vmcnt(1)
	ds_write_b128 v244, v[26:29] offset:8192
	s_waitcnt vmcnt(0)
	ds_write_b128 v245, v[30:33] offset:41984
	s_waitcnt lgkmcnt(0)
	s_barrier
	s_cbranch_vccnz .LBB0_925
	s_add_i32 s40, s35, s12
	s_add_i32 s41, s40, 0xffffff80
	s_sub_i32 s42, s40, 64
	s_cmp_eq_u32 s12, 0
	s_cselect_b32 s40, s36, s41
	v_add_u32_e32 v18, s40, v161
	v_mad_i64_i32 v[18:19], s[40:41], v18, s21, v[146:147]
	s_cselect_b32 s40, s37, s42
	s_nop 0
	v_add_u32_e32 v20, s40, v161
	v_mad_i64_i32 v[22:23], s[40:41], v20, s21, v[146:147]
	global_load_dwordx4 v[18:21], v[18:19], off offset:3648
	s_nop 0
	global_load_dwordx4 v[26:29], v[22:23], off offset:3648
	s_nop 0
	global_load_dwordx4 v[22:25], v[148:149], off
	global_load_dwordx4 v[30:33], v[148:149], off offset:128
	s_branch .LBB0_925

.LBB0_2158:
	s_ashr_i32 s2, s30, 8
	s_lshl_b32 s0, s30, 8
	s_lshl_b32 s33, s2, 14
	s_and_b32 s0, s0, 0x3f00
	v_mov_b32_e32 v50, v1
	s_or_b32 s0, s33, s0
	s_bfe_u32 s34, s30, 0x20006
	v_and_b32_e32 v3, 15, v50
	v_ashrrev_i32_e32 v2, 1, v50
	v_and_b32_e32 v2, 0xffffffe0, v2
	v_or_b32_e32 v4, s0, v3
	v_add_u32_e32 v138, v4, v2
	v_mov_b64_e32 v[4:5], s[60:61]
	v_mad_i64_i32 v[6:7], s[0:1], v138, s19, v[4:5]
	s_lshl_b32 s10, s34, 7
	v_lshl_add_u64 v[6:7], v[6:7], 0, s[10:11]
	v_and_b32_e32 v134, 48, v50
	v_lshl_add_u64 v[6:7], v[6:7], 0, v[134:135]
	global_load_dwordx4 v[10:13], v[6:7], off offset:3136
	global_load_dwordx4 v[14:17], v[6:7], off offset:3200
	s_lshl_b32 s0, s2, 2
	s_lshl_b32 s1, s2, 3
	s_lshl_b32 s35, s34, 1
	s_or_b32 s2, s0, s34
	s_or_b32 s0, s35, s1
	s_ashr_i32 s1, s0, 31
	s_lshl_b32 s31, s34, 6
	s_lshl_b64 s[0:1], s[0:1], 2
	s_add_u32 s0, s88, s0
	s_addc_u32 s1, s89, s1
	global_load_dwordx2 v[6:7], v135, s[0:1] offset:256
	v_cmp_lt_i32_e32 vcc, v148, v149
	v_or_b32_e32 v140, 16, v138
	v_mad_i64_i32 v[18:19], s[0:1], v140, s19, v[4:5]
	v_cndmask_b32_e32 v2, v137, v148, vcc
	v_lshlrev_b32_e32 v156, 2, v2
	v_cmp_lt_i32_e32 vcc, v150, v149
	v_lshl_add_u64 v[18:19], v[18:19], 0, s[10:11]
	v_lshl_add_u64 v[22:23], v[18:19], 0, v[134:135]
	v_cndmask_b32_e32 v8, v137, v150, vcc
	v_lshlrev_b32_e32 v155, 2, v8
	global_load_dwordx4 v[18:21], v[22:23], off offset:3136
	s_mul_i32 s35, s2, 0x208000
	s_mul_hi_i32 s34, s2, 0x208000
	v_ashrrev_i32_e32 v159, 3, v50
	v_mov_b32_e32 v143, v135
	v_and_b32_e32 v157, 63, v50
	v_bfe_u32 v8, v50, 4, 2
	v_lshlrev_b32_e32 v69, 6, v159
	v_mul_lo_u32 v71, v159, s23
	v_lshlrev_b32_e32 v160, 6, v3
	v_mul_u32_u24_e32 v72, 0x48, v3
	v_ashrrev_i32_e32 v139, 31, v138
	v_ashrrev_i32_e32 v141, 31, v140
	v_lshlrev_b32_e32 v158, 2, v8
	v_lshlrev_b32_e32 v164, 1, v71
	v_lshlrev_b32_e32 v165, 1, v72
	v_mov_b32_e32 v71, v135
	v_mov_b32_e32 v72, v135
	v_mov_b32_e32 v73, v135
	v_mov_b32_e32 v74, 0
	v_mov_b32_e32 v75, v135
	v_mov_b32_e32 v76, v135
	v_mov_b32_e32 v77, v135
	v_mov_b32_e32 v78, 0
	v_mov_b32_e32 v79, v135
	v_mov_b32_e32 v80, v135
	v_mov_b32_e32 v81, v135
	v_mov_b32_e32 v90, 0
	v_mov_b32_e32 v91, v135
	v_mov_b32_e32 v92, v135
	v_mov_b32_e32 v93, v135
	v_mov_b32_e32 v94, 0
	v_mov_b32_e32 v95, v135
	v_mov_b32_e32 v96, v135
	v_mov_b32_e32 v97, v135
	v_mov_b32_e32 v98, 0
	v_mov_b32_e32 v99, v135
	v_mov_b32_e32 v100, v135
	v_mov_b32_e32 v101, v135
	v_mov_b32_e32 v102, 0
	v_mov_b32_e32 v103, v135
	v_mov_b32_e32 v104, v135
	v_mov_b32_e32 v105, v135
	v_mov_b32_e32 v106, 0
	v_mov_b32_e32 v107, v135
	v_mov_b32_e32 v108, v135
	v_mov_b32_e32 v109, v135
	v_mov_b32_e32 v110, 0
	v_mov_b32_e32 v111, v135
	v_mov_b32_e32 v112, v135
	v_mov_b32_e32 v113, v135
	v_mov_b32_e32 v118, 0
	v_mov_b32_e32 v119, v135
	v_mov_b32_e32 v120, v135
	v_mov_b32_e32 v121, v135
	v_mov_b32_e32 v122, 0
	s_waitcnt vmcnt(3)
	v_and_b32_e32 v25, 0xffff0000, v10
	v_lshlrev_b32_e32 v24, 16, v10
	v_and_b32_e32 v27, 0xffff0000, v11
	v_lshlrev_b32_e32 v26, 16, v11
	v_pk_mul_f32 v[24:25], v[24:25], s[12:13] op_sel_hi:[1,0]
	v_and_b32_e32 v11, 0xffff0000, v12
	v_lshlrev_b32_e32 v10, 16, v12
	v_pk_mul_f32 v[26:27], v[26:27], s[12:13] op_sel_hi:[1,0]
	v_and_b32_sdwa v9, v24, v152 dst_sel:DWORD dst_unused:UNUSED_PAD src0_sel:WORD_1 src1_sel:DWORD
	v_and_b32_e32 v29, 0xffff0000, v13
	v_lshlrev_b32_e32 v28, 16, v13
	s_waitcnt vmcnt(2)
	v_and_b32_e32 v13, 0xffff0000, v14
	v_lshlrev_b32_e32 v12, 16, v14
	v_pk_mul_f32 v[10:11], v[10:11], s[12:13] op_sel_hi:[1,0]
	v_and_b32_sdwa v2, v25, v152 dst_sel:DWORD dst_unused:UNUSED_PAD src0_sel:WORD_1 src1_sel:DWORD
	v_and_b32_sdwa v14, v27, v152 dst_sel:DWORD dst_unused:UNUSED_PAD src0_sel:WORD_1 src1_sel:DWORD
	v_and_b32_sdwa v30, v26, v152 dst_sel:DWORD dst_unused:UNUSED_PAD src0_sel:WORD_1 src1_sel:DWORD
	v_add3_u32 v9, v24, v9, s20
	v_and_b32_sdwa v32, v11, v152 dst_sel:DWORD dst_unused:UNUSED_PAD src0_sel:WORD_1 src1_sel:DWORD
	v_and_b32_sdwa v33, v10, v152 dst_sel:DWORD dst_unused:UNUSED_PAD src0_sel:WORD_1 src1_sel:DWORD
	v_add3_u32 v38, v25, v2, s20
	v_add3_u32 v39, v27, v14, s20
	v_add3_u32 v40, v26, v30, s20
	v_and_b32_e32 v2, 0xffff0000, v9
	v_add3_u32 v36, v11, v32, s20
	v_add3_u32 v41, v10, v33, s20
	v_and_b32_e32 v14, 0xffff0000, v38
	v_and_b32_e32 v11, 0xffff0000, v39
	v_and_b32_e32 v10, 0xffff0000, v40
	v_mul_f32_e32 v2, v2, v2
	v_pk_mul_f32 v[28:29], v[28:29], s[12:13] op_sel_hi:[1,0]
	v_pk_mul_f32 v[10:11], v[10:11], v[10:11]
	v_fmac_f32_e32 v2, v14, v14
	v_and_b32_sdwa v34, v29, v152 dst_sel:DWORD dst_unused:UNUSED_PAD src0_sel:WORD_1 src1_sel:DWORD
	v_and_b32_sdwa v35, v28, v152 dst_sel:DWORD dst_unused:UNUSED_PAD src0_sel:WORD_1 src1_sel:DWORD
	v_and_b32_e32 v25, 0xffff0000, v36
	v_and_b32_e32 v24, 0xffff0000, v41
	v_add_f32_e32 v2, v10, v2
	v_add3_u32 v34, v29, v34, s20
	v_add3_u32 v35, v28, v35, s20
	v_pk_mul_f32 v[24:25], v[24:25], v[24:25]
	v_add_f32_e32 v2, v11, v2
	v_and_b32_e32 v27, 0xffff0000, v34
	v_and_b32_e32 v26, 0xffff0000, v35
	v_add_f32_e32 v2, v24, v2
	v_pk_mul_f32 v[26:27], v[26:27], v[26:27]
	v_add_f32_e32 v2, v25, v2
	v_add_f32_e32 v2, v26, v2
	v_add_f32_e32 v2, v27, v2
	ds_bpermute_b32 v14, v156, v2
	v_pk_mul_f32 v[10:11], v[12:13], s[12:13] op_sel_hi:[1,0]
	v_and_b32_e32 v31, 0xffff0000, v15
	v_and_b32_sdwa v24, v10, v152 dst_sel:DWORD dst_unused:UNUSED_PAD src0_sel:WORD_1 src1_sel:DWORD
	v_lshlrev_b32_e32 v30, 16, v15
	s_waitcnt lgkmcnt(0)
	v_add_f32_e32 v2, v2, v14
	ds_bpermute_b32 v14, v155, v2
	v_and_b32_sdwa v15, v11, v152 dst_sel:DWORD dst_unused:UNUSED_PAD src0_sel:WORD_1 src1_sel:DWORD
	v_add3_u32 v46, v10, v24, s20
	v_add3_u32 v42, v11, v15, s20
	v_and_b32_e32 v10, 0xffff0000, v46
	s_waitcnt lgkmcnt(0)
	v_add_f32_e32 v2, v2, v14
	s_waitcnt vmcnt(1)
	v_mul_f32_e32 v2, v6, v2
	v_mul_f32_e32 v11, 0x4f800000, v2
	v_cmp_gt_f32_e32 vcc, s21, v2
	v_pk_mul_f32 v[12:13], v[30:31], s[12:13] op_sel_hi:[1,0]
	v_mul_f32_e32 v15, v10, v10
	v_cndmask_b32_e32 v2, v2, v11, vcc
	v_and_b32_e32 v11, 0xffff0000, v42
	v_fmac_f32_e32 v15, v11, v11
	v_and_b32_sdwa v10, v13, v152 dst_sel:DWORD dst_unused:UNUSED_PAD src0_sel:WORD_1 src1_sel:DWORD
	v_and_b32_sdwa v11, v12, v152 dst_sel:DWORD dst_unused:UNUSED_PAD src0_sel:WORD_1 src1_sel:DWORD
	v_add3_u32 v43, v13, v10, s20
	v_add3_u32 v47, v12, v11, s20
	v_and_b32_e32 v11, 0xffff0000, v43
	v_and_b32_e32 v10, 0xffff0000, v47
	v_pk_mul_f32 v[10:11], v[10:11], v[10:11]
	v_sqrt_f32_e32 v14, v2
	v_add_f32_e32 v10, v10, v15
	v_add_f32_e32 v12, v11, v10
	v_and_b32_e32 v11, 0xffff0000, v16
	v_lshlrev_b32_e32 v10, 16, v16
	v_pk_mul_f32 v[10:11], v[10:11], s[12:13] op_sel_hi:[1,0]
	v_add_u32_e32 v24, -1, v14
	v_and_b32_sdwa v13, v11, v152 dst_sel:DWORD dst_unused:UNUSED_PAD src0_sel:WORD_1 src1_sel:DWORD
	v_and_b32_sdwa v15, v10, v152 dst_sel:DWORD dst_unused:UNUSED_PAD src0_sel:WORD_1 src1_sel:DWORD
	v_add3_u32 v44, v11, v13, s20
	v_add3_u32 v48, v10, v15, s20
	v_and_b32_e32 v11, 0xffff0000, v44
	v_and_b32_e32 v10, 0xffff0000, v48
	v_pk_mul_f32 v[10:11], v[10:11], v[10:11]
	v_fma_f32 v25, -v24, v14, v2
	v_add_f32_e32 v10, v10, v12
	v_add_f32_e32 v12, v11, v10
	v_and_b32_e32 v11, 0xffff0000, v17
	v_lshlrev_b32_e32 v10, 16, v17
	v_pk_mul_f32 v[10:11], v[10:11], s[12:13] op_sel_hi:[1,0]
	v_cmp_ge_f32_e64 s[0:1], 0, v25
	v_and_b32_sdwa v13, v11, v152 dst_sel:DWORD dst_unused:UNUSED_PAD src0_sel:WORD_1 src1_sel:DWORD
	v_and_b32_sdwa v15, v10, v152 dst_sel:DWORD dst_unused:UNUSED_PAD src0_sel:WORD_1 src1_sel:DWORD
	v_add3_u32 v45, v11, v13, s20
	v_add3_u32 v49, v10, v15, s20
	v_and_b32_e32 v11, 0xffff0000, v45
	v_and_b32_e32 v10, 0xffff0000, v49
	v_pk_mul_f32 v[10:11], v[10:11], v[10:11]
	v_add_u32_e32 v13, 1, v14
	v_add_f32_e32 v10, v10, v12
	v_add_f32_e32 v10, v11, v10
	ds_bpermute_b32 v11, v156, v10
	v_cndmask_b32_e64 v12, v14, v24, s[0:1]
	v_fma_f32 v14, -v13, v14, v2
	v_cmp_lt_f32_e64 s[0:1], 0, v14
	v_perm_b32 v37, v34, v35, s24
	s_waitcnt lgkmcnt(0)
	v_add_f32_e32 v10, v10, v11
	ds_bpermute_b32 v11, v155, v10
	v_cndmask_b32_e64 v12, v12, v13, s[0:1]
	v_mul_f32_e32 v13, 0x37800000, v12
	v_cndmask_b32_e32 v14, v12, v13, vcc
	v_cmp_class_f32_e64 s[0:1], v2, v151
	s_waitcnt lgkmcnt(0)
	v_add_f32_e32 v10, v10, v11
	v_mul_f32_e32 v15, v7, v10
	global_load_dwordx4 v[10:13], v[22:23], off offset:3200
	v_mul_f32_e32 v16, 0x4f800000, v15
	v_cmp_gt_f32_e32 vcc, s21, v15
	v_cndmask_b32_e64 v2, v14, v2, s[0:1]
	s_waitcnt vmcnt(1)
	v_lshlrev_b32_e32 v14, 16, v18
	v_cndmask_b32_e32 v16, v15, v16, vcc
	v_and_b32_e32 v15, 0xffff0000, v18
	v_pk_mul_f32 v[14:15], v[14:15], s[12:13] op_sel_hi:[1,0]
	v_sqrt_f32_e32 v17, v16
	v_and_b32_sdwa v24, v14, v152 dst_sel:DWORD dst_unused:UNUSED_PAD src0_sel:WORD_1 src1_sel:DWORD
	v_and_b32_sdwa v18, v15, v152 dst_sel:DWORD dst_unused:UNUSED_PAD src0_sel:WORD_1 src1_sel:DWORD
	v_add3_u32 v54, v14, v24, s20
	v_add3_u32 v51, v15, v18, s20
	v_and_b32_e32 v14, 0xffff0000, v54
	v_mul_f32_e32 v18, v14, v14
	v_and_b32_e32 v14, 0xffff0000, v51
	v_fmac_f32_e32 v18, v14, v14
	v_and_b32_e32 v15, 0xffff0000, v19
	v_lshlrev_b32_e32 v14, 16, v19
	v_pk_mul_f32 v[14:15], v[14:15], s[12:13] op_sel_hi:[1,0]
	v_add_u32_e32 v22, -1, v17
	v_and_b32_sdwa v19, v15, v152 dst_sel:DWORD dst_unused:UNUSED_PAD src0_sel:WORD_1 src1_sel:DWORD
	v_and_b32_sdwa v24, v14, v152 dst_sel:DWORD dst_unused:UNUSED_PAD src0_sel:WORD_1 src1_sel:DWORD
	v_add3_u32 v55, v15, v19, s20
	v_add3_u32 v56, v14, v24, s20
	v_and_b32_e32 v15, 0xffff0000, v55
	v_and_b32_e32 v14, 0xffff0000, v56
	v_pk_mul_f32 v[14:15], v[14:15], v[14:15]
	v_fma_f32 v23, -v22, v17, v16
	v_add_f32_e32 v14, v14, v18
	v_add_f32_e32 v18, v15, v14
	v_and_b32_e32 v15, 0xffff0000, v20
	v_lshlrev_b32_e32 v14, 16, v20
	v_pk_mul_f32 v[14:15], v[14:15], s[12:13] op_sel_hi:[1,0]
	v_cmp_ge_f32_e64 s[0:1], 0, v23
	v_and_b32_sdwa v19, v15, v152 dst_sel:DWORD dst_unused:UNUSED_PAD src0_sel:WORD_1 src1_sel:DWORD
	v_and_b32_sdwa v20, v14, v152 dst_sel:DWORD dst_unused:UNUSED_PAD src0_sel:WORD_1 src1_sel:DWORD
	v_add3_u32 v57, v15, v19, s20
	v_add3_u32 v58, v14, v20, s20
	v_and_b32_e32 v15, 0xffff0000, v57
	v_and_b32_e32 v14, 0xffff0000, v58
	v_pk_mul_f32 v[14:15], v[14:15], v[14:15]
	v_xor_b32_e32 v2, 0x80000000, v2
	v_add_f32_e32 v14, v14, v18
	v_add_f32_e32 v18, v15, v14
	v_and_b32_e32 v15, 0xffff0000, v21
	v_lshlrev_b32_e32 v14, 16, v21
	v_pk_mul_f32 v[14:15], v[14:15], s[12:13] op_sel_hi:[1,0]
	v_perm_b32 v36, v36, v41, s24
	v_and_b32_sdwa v19, v15, v152 dst_sel:DWORD dst_unused:UNUSED_PAD src0_sel:WORD_1 src1_sel:DWORD
	v_and_b32_sdwa v20, v14, v152 dst_sel:DWORD dst_unused:UNUSED_PAD src0_sel:WORD_1 src1_sel:DWORD
	v_add3_u32 v59, v15, v19, s20
	v_add3_u32 v60, v14, v20, s20
	v_and_b32_e32 v15, 0xffff0000, v59
	v_and_b32_e32 v14, 0xffff0000, v60
	v_pk_mul_f32 v[14:15], v[14:15], v[14:15]
	v_add_u32_e32 v19, 1, v17
	v_add_f32_e32 v14, v14, v18
	v_add_f32_e32 v14, v15, v14
	ds_bpermute_b32 v15, v156, v14
	v_cndmask_b32_e64 v18, v17, v22, s[0:1]
	v_fma_f32 v17, -v19, v17, v16
	v_cmp_lt_f32_e64 s[0:1], 0, v17
	v_perm_b32 v35, v39, v40, s24
	s_waitcnt lgkmcnt(0)
	v_add_f32_e32 v14, v14, v15
	ds_bpermute_b32 v15, v155, v14
	v_cndmask_b32_e64 v17, v18, v19, s[0:1]
	v_mul_f32_e32 v18, 0x37800000, v17
	v_cndmask_b32_e32 v17, v17, v18, vcc
	v_cmp_class_f32_e64 s[0:1], v16, v151
	s_waitcnt lgkmcnt(0)
	v_add_f32_e32 v14, v14, v15
	v_mul_f32_e32 v6, v6, v14
	v_mul_f32_e32 v14, 0x4f800000, v6
	v_cmp_gt_f32_e32 vcc, s21, v6
	v_perm_b32 v34, v38, v9, s24
	v_perm_b32 v41, v59, v60, s24
	v_cndmask_b32_e32 v18, v6, v14, vcc
	v_sqrt_f32_e32 v19, v18
	v_cndmask_b32_e64 v6, v17, v16, s[0:1]
	v_xor_b32_e32 v6, 0x80000000, v6
	s_waitcnt vmcnt(0)
	v_and_b32_e32 v15, 0xffff0000, v10
	v_lshlrev_b32_e32 v14, 16, v10
	v_pk_mul_f32 v[14:15], v[14:15], s[12:13] op_sel_hi:[1,0]
	v_add_u32_e32 v16, -1, v19
	v_and_b32_sdwa v20, v14, v152 dst_sel:DWORD dst_unused:UNUSED_PAD src0_sel:WORD_1 src1_sel:DWORD
	v_and_b32_sdwa v10, v15, v152 dst_sel:DWORD dst_unused:UNUSED_PAD src0_sel:WORD_1 src1_sel:DWORD
	v_add3_u32 v62, v14, v20, s20
	v_add3_u32 v61, v15, v10, s20
	v_and_b32_e32 v10, 0xffff0000, v62
	v_mul_f32_e32 v20, v10, v10
	v_and_b32_e32 v10, 0xffff0000, v61
	v_and_b32_e32 v15, 0xffff0000, v11
	v_lshlrev_b32_e32 v14, 16, v11
	v_fmac_f32_e32 v20, v10, v10
	v_pk_mul_f32 v[10:11], v[14:15], s[12:13] op_sel_hi:[1,0]
	v_fma_f32 v17, -v16, v19, v18
	v_and_b32_sdwa v14, v11, v152 dst_sel:DWORD dst_unused:UNUSED_PAD src0_sel:WORD_1 src1_sel:DWORD
	v_and_b32_sdwa v15, v10, v152 dst_sel:DWORD dst_unused:UNUSED_PAD src0_sel:WORD_1 src1_sel:DWORD
	v_add3_u32 v63, v11, v14, s20
	v_add3_u32 v64, v10, v15, s20
	v_and_b32_e32 v11, 0xffff0000, v63
	v_and_b32_e32 v10, 0xffff0000, v64
	v_pk_mul_f32 v[10:11], v[10:11], v[10:11]
	v_cmp_ge_f32_e64 s[0:1], 0, v17
	v_add_f32_e32 v10, v10, v20
	v_add_f32_e32 v14, v11, v10
	v_and_b32_e32 v11, 0xffff0000, v12
	v_lshlrev_b32_e32 v10, 16, v12
	v_pk_mul_f32 v[10:11], v[10:11], s[12:13] op_sel_hi:[1,0]
	v_perm_b32 v40, v57, v58, s24
	v_and_b32_sdwa v12, v11, v152 dst_sel:DWORD dst_unused:UNUSED_PAD src0_sel:WORD_1 src1_sel:DWORD
	v_and_b32_sdwa v15, v10, v152 dst_sel:DWORD dst_unused:UNUSED_PAD src0_sel:WORD_1 src1_sel:DWORD
	v_add3_u32 v65, v11, v12, s20
	v_add3_u32 v66, v10, v15, s20
	v_and_b32_e32 v11, 0xffff0000, v65
	v_and_b32_e32 v10, 0xffff0000, v66
	v_pk_mul_f32 v[10:11], v[10:11], v[10:11]
	v_perm_b32 v39, v55, v56, s24
	v_add_f32_e32 v10, v10, v14
	v_add_f32_e32 v12, v11, v10
	v_and_b32_e32 v11, 0xffff0000, v13
	v_lshlrev_b32_e32 v10, 16, v13
	v_pk_mul_f32 v[10:11], v[10:11], s[12:13] op_sel_hi:[1,0]
	v_perm_b32 v38, v51, v54, s24
	v_and_b32_sdwa v13, v11, v152 dst_sel:DWORD dst_unused:UNUSED_PAD src0_sel:WORD_1 src1_sel:DWORD
	v_and_b32_sdwa v14, v10, v152 dst_sel:DWORD dst_unused:UNUSED_PAD src0_sel:WORD_1 src1_sel:DWORD
	v_add3_u32 v67, v11, v13, s20
	v_add3_u32 v68, v10, v14, s20
	v_and_b32_e32 v11, 0xffff0000, v67
	v_and_b32_e32 v10, 0xffff0000, v68
	v_pk_mul_f32 v[10:11], v[10:11], v[10:11]
	v_add_u32_e32 v13, 1, v19
	v_add_f32_e32 v10, v10, v12
	v_add_f32_e32 v10, v11, v10
	ds_bpermute_b32 v11, v156, v10
	v_fma_f32 v14, -v13, v19, v18
	v_cndmask_b32_e64 v12, v19, v16, s[0:1]
	v_cmp_lt_f32_e64 s[0:1], 0, v14
	v_mov_b32_e32 v9, v6
	s_waitcnt lgkmcnt(0)
	v_add_f32_e32 v10, v10, v11
	ds_bpermute_b32 v11, v155, v10
	v_cndmask_b32_e64 v12, v12, v13, s[0:1]
	v_mul_f32_e32 v13, 0x37800000, v12
	v_cndmask_b32_e32 v12, v12, v13, vcc
	v_cmp_class_f32_e64 s[0:1], v18, v151
	s_waitcnt lgkmcnt(0)
	v_add_f32_e32 v10, v10, v11
	v_mul_f32_e32 v7, v7, v10
	v_mul_f32_e32 v10, 0x4f800000, v7
	v_cmp_gt_f32_e32 vcc, s21, v7
	v_perm_b32 v45, v45, v49, s24
	v_perm_b32 v44, v44, v48, s24
	v_cndmask_b32_e32 v7, v7, v10, vcc
	v_sqrt_f32_e32 v11, v7
	v_cndmask_b32_e64 v10, v12, v18, s[0:1]
	v_xor_b32_e32 v10, 0x80000000, v10
	v_perm_b32 v43, v43, v47, s24
	v_add_u32_e32 v12, -1, v11
	v_fma_f32 v13, -v12, v11, v7
	v_cmp_ge_f32_e64 s[0:1], 0, v13
	v_add_u32_e32 v13, 1, v11
	v_perm_b32 v42, v42, v46, s24
	v_cndmask_b32_e64 v12, v11, v12, s[0:1]
	v_fma_f32 v11, -v13, v11, v7
	v_cmp_lt_f32_e64 s[0:1], 0, v11
	v_perm_b32 v49, v67, v68, s24
	v_perm_b32 v48, v65, v66, s24
	v_cndmask_b32_e64 v11, v12, v13, s[0:1]
	v_mul_f32_e32 v12, 0x37800000, v11
	v_cndmask_b32_e32 v11, v11, v12, vcc
	v_cmp_class_f32_e32 vcc, v7, v151
	s_add_u32 s0, s3, s35
	s_addc_u32 s1, s13, s34
	v_cndmask_b32_e32 v7, v11, v7, vcc
	s_and_b32 s36, s30, 0xffffff00
	v_xor_b32_e32 v14, 0x80000000, v7
	v_add_u32_e32 v7, s36, v159
	v_add_u32_e32 v11, 0x8000, v7
	v_mad_i64_i32 v[12:13], s[34:35], v11, s19, v[4:5]
	v_lshlrev_b32_e32 v11, 3, v50
	v_add_u32_e32 v7, 0x8040, v7
	v_and_b32_e32 v11, 56, v11
	v_mov_b64_e32 v[16:17], s[0:1]
	v_mad_i64_i32 v[4:5], s[0:1], v7, s19, v[4:5]
	v_lshl_add_u64 v[12:13], v[12:13], 0, s[10:11]
	v_lshlrev_b32_e32 v142, 1, v11
	v_lshl_add_u64 v[4:5], v[4:5], 0, s[10:11]
	v_lshl_add_u64 v[12:13], v[12:13], 0, v[142:143]
	v_mad_i64_i32 v[16:17], s[0:1], v159, s22, v[16:17]
	v_lshl_add_u64 v[4:5], v[4:5], 0, v[142:143]
	v_lshl_add_u64 v[16:17], v[16:17], 0, v[142:143]
	global_load_dwordx4 v[18:21], v[12:13], off offset:3648
	global_load_dwordx4 v[22:25], v[16:17], off
	global_load_dwordx4 v[26:29], v[4:5], off offset:3648
	global_load_dwordx4 v[30:33], v[16:17], off offset:128
	v_mad_i64_i32 v[52:53], s[34:35], v159, s22, 0
	v_lshrrev_b32_e32 v4, 1, v159
	s_add_i32 s34, s36, 0x8080
	s_add_i32 s35, s36, 0x80c0
	v_xor_b32_e32 v4, v4, v50
	s_add_u32 s0, s60, s10
	v_lshlrev_b32_e32 v4, 3, v4
	s_addc_u32 s1, s61, 0
	v_and_b32_e32 v70, 56, v4
	v_bfe_u32 v4, v50, 1, 3
	v_lshl_add_u64 v[144:145], s[0:1], 0, v[142:143]
	v_mad_i64_i32 v[52:53], s[0:1], s2, v153, v[52:53]
	v_and_b32_e32 v50, 7, v50
	v_xor_b32_e32 v5, v8, v4
	v_bitop3_b32 v3, v8, v4, 4 bitop3:0x36
	v_lshl_or_b32 v52, v50, 4, v52
	v_lshlrev_b32_e32 v161, 3, v5
	v_lshlrev_b32_e32 v162, 3, v3
	v_mov_b32_e32 v3, v2
	v_mov_b32_e32 v4, v2
	v_mov_b32_e32 v5, v2
	v_mov_b32_e32 v11, v10
	v_mov_b32_e32 v12, v10
	v_mov_b32_e32 v13, v10
	v_mov_b32_e32 v7, v6
	v_mov_b32_e32 v8, v6
	v_mov_b32_e32 v15, v14
	v_mov_b32_e32 v16, v14
	v_mov_b32_e32 v17, v14
	v_perm_b32 v47, v63, v64, s24
	v_perm_b32 v46, v61, v62, s24
	v_lshl_add_u64 v[146:147], s[8:9], 0, v[52:53]
	v_lshlrev_b32_e32 v143, 1, v69
	v_lshlrev_b32_e32 v163, 1, v70
	s_mov_b32 s10, 0
	s_mov_b32 s36, 0
	v_mov_b32_e32 v66, 0
	v_mov_b32_e32 v67, v135
	v_mov_b32_e32 v68, v135
	v_mov_b32_e32 v69, v135
	v_mov_b32_e32 v50, 0
	v_mov_b32_e32 v51, v135
	v_mov_b32_e32 v52, v135
	v_mov_b32_e32 v53, v135
	v_mov_b32_e32 v54, 0
	v_mov_b32_e32 v55, v135
	v_mov_b32_e32 v56, v135
	v_mov_b32_e32 v57, v135
	v_mov_b32_e32 v58, 0
	v_mov_b32_e32 v59, v135
	v_mov_b32_e32 v60, v135
	v_mov_b32_e32 v61, v135
	v_mov_b32_e32 v62, 0
	v_mov_b32_e32 v63, v135
	v_mov_b32_e32 v64, v135
	v_mov_b32_e32 v65, v135
	v_mov_b32_e32 v70, 0
	v_mov_b32_e32 v123, v135
	v_mov_b32_e32 v124, v135
	v_mov_b32_e32 v125, v135
	v_mov_b32_e32 v82, 0
	v_mov_b32_e32 v83, v135
	v_mov_b32_e32 v84, v135
	v_mov_b32_e32 v85, v135
	v_mov_b32_e32 v86, 0
	v_mov_b32_e32 v87, v135
	v_mov_b32_e32 v88, v135
	v_mov_b32_e32 v89, v135
	v_mov_b32_e32 v114, 0
	v_mov_b32_e32 v115, v135
	v_mov_b32_e32 v116, v135
	v_mov_b32_e32 v117, v135
	v_mov_b32_e32 v126, 0
	v_mov_b32_e32 v127, v135
	v_mov_b32_e32 v128, v135
	v_mov_b32_e32 v129, v135
	v_lshlrev_b32_e32 v246, 1, v160
	v_lshl_add_u32 v247, v162, 1, v246
	v_lshl_add_u32 v246, v161, 1, v246
	v_lshl_add_u32 v248, v158, 1, v165
	v_add_u32_e32 v244, v143, v163
	v_add_u32_e32 v245, v164, v142
	v_mov_b64_e32 v[240:241], s[4:5]
	v_mov_b64_e32 v[242:243], s[6:7]
	s_movk_i32 s99, 0x4800
	v_lshlrev_b32_e32 v134, 1, v158
	s_barrier
	s_branch .LBB0_2160
.LBB0_2159:
	ds_read_b128 v[130:133], v246
	ds_read_b128 v[166:169], v246 offset:2048
	s_waitcnt lgkmcnt(1)
	v_mfma_f32_16x16x32_bf16 v[170:173], v[130:133], v[34:37], v[2:5]
	ds_read_b128 v[182:185], v247 offset:2048
	v_mfma_f32_16x16x32_bf16 v[178:181], v[130:133], v[38:41], v[10:13]
	ds_read_b128 v[130:133], v247
	s_nop 2
	s_nop 1
	v_exp_f32_e32 v198, v170
	v_exp_f32_e32 v199, v173
	s_waitcnt lgkmcnt(2)
	v_mfma_f32_16x16x32_bf16 v[174:177], v[166:169], v[34:37], v[2:5]
	v_exp_f32_e32 v178, v178
	ds_read_b64 v[214:215], v248 offset:37376
	ds_read_b64 v[216:217], v248 offset:37408
	v_mfma_f32_16x16x32_bf16 v[166:169], v[166:169], v[38:41], v[10:13]
	ds_read_b64 v[218:219], v248 offset:39680
	ds_read_b64 v[220:221], v248 offset:39712
	s_nop 2
	v_exp_f32_e32 v202, v174
	v_exp_f32_e32 v174, v171
	s_waitcnt lgkmcnt(4)
	v_mfma_f32_16x16x32_bf16 v[186:189], v[130:133], v[42:45], v[6:9]
	v_exp_f32_e32 v203, v175
	v_exp_f32_e32 v211, v166
	v_exp_f32_e32 v166, v179
	v_mfma_f32_16x16x32_bf16 v[194:197], v[130:133], v[46:49], v[14:17]
	ds_read_b128 v[130:133], v246 offset:4096
	v_exp_f32_e32 v179, v167
	v_exp_f32_e32 v167, v180
	v_exp_f32_e32 v180, v168
	v_exp_f32_e32 v168, v181
	v_exp_f32_e32 v169, v169
	v_exp_f32_e32 v175, v172
	v_cvt_pk_bf16_f32 v166, v178, v166
	v_cvt_pk_bf16_f32 v167, v167, v168
	v_cvt_pk_bf16_f32 v168, v211, v179
	v_cvt_pk_bf16_f32 v169, v180, v169
	ds_read_b64 v[178:179], v248 offset:32768
	ds_read_b64 v[180:181], v248 offset:32800
	ds_read_b64 v[210:211], v248 offset:35072
	ds_read_b64 v[212:213], v248 offset:35104
	ds_read_b128 v[170:173], v246 offset:6144
	v_cvt_pk_bf16_f32 v174, v198, v174
	v_cvt_pk_bf16_f32 v175, v175, v199
	s_waitcnt lgkmcnt(5)
	v_mfma_f32_16x16x32_bf16 v[198:201], v[130:133], v[34:37], v[2:5]
	v_exp_f32_e32 v229, v188
	v_exp_f32_e32 v204, v176
	v_exp_f32_e32 v177, v177
	v_mfma_f32_16x16x32_bf16 v[206:209], v[130:133], v[38:41], v[10:13]
	v_exp_f32_e32 v186, v186
	v_mfma_f32_16x16x32_bf16 v[190:193], v[182:185], v[42:45], v[6:9]
	v_exp_f32_e32 v187, v187
	v_exp_f32_e32 v194, v194
	v_cvt_pk_bf16_f32 v176, v202, v203
	v_mfma_f32_16x16x32_bf16 v[182:185], v[182:185], v[46:49], v[14:17]
	v_cvt_pk_bf16_f32 v177, v204, v177
	s_nop 2
	v_exp_f32_e32 v190, v190
	v_exp_f32_e32 v191, v191
	v_mfma_f32_16x16x32_bf16 v[86:89], v[240:243], v[166:169], v[86:89]
	v_exp_f32_e32 v192, v192
	v_exp_f32_e32 v185, v185
	ds_read_b128 v[222:225], v247 offset:4096
	s_waitcnt lgkmcnt(4)
	v_mfma_f32_16x16x32_bf16 v[78:81], v[178:181], v[166:169], v[78:81]
	s_add_i32 s36, s36, 2
	s_addk_i32 s10, 0x80
	v_lshl_add_u64 v[146:147], v[146:147], 0, s[14:15]
	s_waitcnt lgkmcnt(2)
	v_mfma_f32_16x16x32_bf16 v[74:77], v[210:213], v[166:169], v[74:77]
	s_and_b64 vcc, exec, s[0:1]
	v_mfma_f32_16x16x32_bf16 v[70:73], v[214:217], v[166:169], v[70:73]
	v_mfma_f32_16x16x32_bf16 v[62:65], v[218:221], v[166:169], v[62:65]
	v_exp_f32_e32 v167, v189
	v_exp_f32_e32 v169, v193
	v_cvt_pk_bf16_f32 v166, v186, v187
	s_waitcnt lgkmcnt(1)
	v_mfma_f32_16x16x32_bf16 v[202:205], v[170:173], v[34:37], v[2:5]
	v_cvt_pk_bf16_f32 v167, v229, v167
	v_exp_f32_e32 v229, v182
	v_exp_f32_e32 v182, v195
	v_exp_f32_e32 v195, v183
	v_exp_f32_e32 v183, v196
	v_exp_f32_e32 v196, v184
	v_exp_f32_e32 v184, v197
	v_cvt_pk_bf16_f32 v168, v190, v191
	v_cvt_pk_bf16_f32 v169, v192, v169
	v_cvt_pk_bf16_f32 v182, v194, v182
	v_cvt_pk_bf16_f32 v183, v183, v184
	v_cvt_pk_bf16_f32 v184, v229, v195
	v_cvt_pk_bf16_f32 v185, v196, v185
	v_mfma_f32_16x16x32_bf16 v[170:173], v[170:173], v[38:41], v[10:13]
	v_exp_f32_e32 v194, v198
	v_exp_f32_e32 v195, v202
	v_exp_f32_e32 v196, v199
	v_mfma_f32_16x16x32_bf16 v[122:125], v[178:181], v[174:177], v[122:125]
	v_exp_f32_e32 v198, v205
	v_exp_f32_e32 v197, v201
	v_mfma_f32_16x16x32_bf16 v[102:105], v[178:181], v[166:169], v[102:105]
	v_mfma_f32_16x16x32_bf16 v[58:61], v[178:181], v[182:185], v[58:61]
	v_exp_f32_e32 v180, v203
	v_exp_f32_e32 v181, v204
	v_exp_f32_e32 v179, v200
	v_mfma_f32_16x16x32_bf16 v[126:129], v[240:243], v[174:177], v[126:129]
	v_cvt_pk_bf16_f32 v178, v194, v196
	v_cvt_pk_bf16_f32 v180, v195, v180
	v_cvt_pk_bf16_f32 v181, v181, v198
	v_mfma_f32_16x16x32_bf16 v[118:121], v[210:213], v[174:177], v[118:121]
	v_exp_f32_e32 v194, v206
	v_exp_f32_e32 v195, v170
	v_exp_f32_e32 v170, v207
	v_mfma_f32_16x16x32_bf16 v[110:113], v[214:217], v[174:177], v[110:113]
	v_exp_f32_e32 v198, v172
	v_cvt_pk_bf16_f32 v179, v179, v197
	v_exp_f32_e32 v196, v171
	v_mfma_f32_16x16x32_bf16 v[106:109], v[218:221], v[174:177], v[106:109]
	ds_read_b128 v[174:177], v247 offset:6144
	v_exp_f32_e32 v197, v208
	ds_read_b128 v[202:205], v246 offset:14336
	v_mfma_f32_16x16x32_bf16 v[114:117], v[240:243], v[166:169], v[114:117]
	v_mfma_f32_16x16x32_bf16 v[98:101], v[210:213], v[166:169], v[98:101]
	v_mfma_f32_16x16x32_bf16 v[94:97], v[214:217], v[166:169], v[94:97]
	v_mfma_f32_16x16x32_bf16 v[90:93], v[218:221], v[166:169], v[90:93]
	v_exp_f32_e32 v169, v173
	v_exp_f32_e32 v167, v209
	v_cvt_pk_bf16_f32 v166, v194, v170
	v_mfma_f32_16x16x32_bf16 v[82:85], v[240:243], v[182:185], v[82:85]
	v_cvt_pk_bf16_f32 v169, v198, v169
	v_mfma_f32_16x16x32_bf16 v[54:57], v[210:213], v[182:185], v[54:57]
	ds_read_b64 v[170:171], v248 offset:32832
	ds_read_b64 v[172:173], v248 offset:32864
	v_cvt_pk_bf16_f32 v167, v197, v167
	v_mfma_f32_16x16x32_bf16 v[50:53], v[214:217], v[182:185], v[50:53]
	v_cvt_pk_bf16_f32 v168, v195, v196
	ds_read_b64 v[194:195], v248 offset:37440
	ds_read_b64 v[196:197], v248 offset:37472
	ds_read_b64 v[198:199], v248 offset:39744
	ds_read_b64 v[200:201], v248 offset:39776
	v_mfma_f32_16x16x32_bf16 v[66:69], v[218:221], v[182:185], v[66:69]
	ds_read_b64 v[182:183], v248 offset:35136
	ds_read_b64 v[184:185], v248 offset:35168
	s_waitcnt lgkmcnt(10)
	v_mfma_f32_16x16x32_bf16 v[186:189], v[222:225], v[42:45], v[6:9]
	ds_read_b64 v[214:215], v248 offset:46592
	ds_read_b64 v[216:217], v248 offset:46624
	s_waitcnt lgkmcnt(11)
	v_mfma_f32_16x16x32_bf16 v[190:193], v[174:177], v[42:45], v[6:9]
	ds_read_b64 v[218:219], v248 offset:48896
	ds_read_b64 v[220:221], v248 offset:48928
	s_nop 1
	v_exp_f32_e32 v186, v186
	v_exp_f32_e32 v187, v187
	v_mfma_f32_16x16x32_bf16 v[222:225], v[222:225], v[46:49], v[14:17]
	v_exp_f32_e32 v188, v188
	s_nop 0
	v_exp_f32_e32 v190, v190
	v_exp_f32_e32 v191, v191
	v_mfma_f32_16x16x32_bf16 v[174:177], v[174:177], v[46:49], v[14:17]
	v_exp_f32_e32 v189, v189
	v_exp_f32_e32 v192, v192
	v_exp_f32_e32 v193, v193
	v_mfma_f32_16x16x32_bf16 v[126:129], v[240:243], v[178:181], v[126:129]
	v_cvt_pk_bf16_f32 v186, v186, v187
	v_cvt_pk_bf16_f32 v187, v188, v189
	v_cvt_pk_bf16_f32 v188, v190, v191
	v_mfma_f32_16x16x32_bf16 v[86:89], v[240:243], v[166:169], v[86:89]
	v_exp_f32_e32 v190, v222
	v_exp_f32_e32 v174, v174
	v_exp_f32_e32 v191, v223
	s_waitcnt lgkmcnt(10)
	v_mfma_f32_16x16x32_bf16 v[122:125], v[170:173], v[178:181], v[122:125]
	v_exp_f32_e32 v175, v175
	v_exp_f32_e32 v176, v176
	v_cvt_pk_bf16_f32 v189, v192, v193
	v_mfma_f32_16x16x32_bf16 v[78:81], v[170:173], v[166:169], v[78:81]
	s_waitcnt lgkmcnt(4)
	v_mfma_f32_16x16x32_bf16 v[118:121], v[182:185], v[178:181], v[118:121]
	v_mfma_f32_16x16x32_bf16 v[74:77], v[182:185], v[166:169], v[74:77]
	v_mfma_f32_16x16x32_bf16 v[110:113], v[194:197], v[178:181], v[110:113]
	v_mfma_f32_16x16x32_bf16 v[70:73], v[194:197], v[166:169], v[70:73]
	v_mfma_f32_16x16x32_bf16 v[106:109], v[198:201], v[178:181], v[106:109]
	v_exp_f32_e32 v178, v224
	v_mfma_f32_16x16x32_bf16 v[62:65], v[198:201], v[166:169], v[62:65]
	v_exp_f32_e32 v167, v225
	v_exp_f32_e32 v169, v177
	v_cvt_pk_bf16_f32 v166, v190, v191
	v_cvt_pk_bf16_f32 v168, v174, v175
	v_cvt_pk_bf16_f32 v167, v178, v167
	v_cvt_pk_bf16_f32 v169, v176, v169
	v_mfma_f32_16x16x32_bf16 v[102:105], v[170:173], v[186:189], v[102:105]
	ds_read_b128 v[222:225], v247 offset:12288
	v_mfma_f32_16x16x32_bf16 v[82:85], v[240:243], v[166:169], v[82:85]
	v_mfma_f32_16x16x32_bf16 v[58:61], v[170:173], v[166:169], v[58:61]
	ds_read_b128 v[170:173], v246 offset:8192
	v_mfma_f32_16x16x32_bf16 v[54:57], v[182:185], v[166:169], v[54:57]
	v_mfma_f32_16x16x32_bf16 v[50:53], v[194:197], v[166:169], v[50:53]
	v_mfma_f32_16x16x32_bf16 v[66:69], v[198:201], v[166:169], v[66:69]
	ds_read_b128 v[166:169], v246 offset:10240
	s_waitcnt lgkmcnt(1)
	v_mfma_f32_16x16x32_bf16 v[174:177], v[170:173], v[34:37], v[2:5]
	s_waitcnt lgkmcnt(0)
	v_mfma_f32_16x16x32_bf16 v[178:181], v[166:169], v[34:37], v[2:5]
	s_nop 5
	v_exp_f32_e32 v174, v174
	v_mfma_f32_16x16x32_bf16 v[170:173], v[170:173], v[38:41], v[10:13]
	v_exp_f32_e32 v206, v178
	v_exp_f32_e32 v175, v175
	v_exp_f32_e32 v207, v179
	v_mfma_f32_16x16x32_bf16 v[166:169], v[166:169], v[38:41], v[10:13]
	v_exp_f32_e32 v176, v176
	s_nop 2
	v_exp_f32_e32 v170, v170
	v_exp_f32_e32 v208, v180
	v_mfma_f32_16x16x32_bf16 v[114:117], v[240:243], v[186:189], v[114:117]
	v_exp_f32_e32 v177, v177
	v_exp_f32_e32 v211, v166
	v_exp_f32_e32 v166, v171
	v_exp_f32_e32 v171, v167
	v_exp_f32_e32 v167, v172
	v_exp_f32_e32 v172, v168
	v_exp_f32_e32 v168, v173
	v_exp_f32_e32 v169, v169
	v_mfma_f32_16x16x32_bf16 v[98:101], v[182:185], v[186:189], v[98:101]
	ds_read_b128 v[182:185], v247 offset:8192
	v_cvt_pk_bf16_f32 v166, v170, v166
	v_cvt_pk_bf16_f32 v167, v167, v168
	v_mfma_f32_16x16x32_bf16 v[94:97], v[194:197], v[186:189], v[94:97]
	v_cvt_pk_bf16_f32 v168, v211, v171
	v_cvt_pk_bf16_f32 v169, v172, v169
	ds_read_b64 v[170:171], v248 offset:41984
	ds_read_b64 v[172:173], v248 offset:42016
	v_mfma_f32_16x16x32_bf16 v[90:93], v[198:201], v[186:189], v[90:93]
	ds_read_b128 v[186:189], v247 offset:10240
	ds_read_b64 v[210:211], v248 offset:44288
	ds_read_b64 v[212:213], v248 offset:44320
	ds_read_b128 v[198:201], v246 offset:12288
	s_waitcnt lgkmcnt(6)
	v_mfma_f32_16x16x32_bf16 v[190:193], v[182:185], v[42:45], v[6:9]
	v_exp_f32_e32 v209, v181
	v_cvt_pk_bf16_f32 v174, v174, v175
	v_cvt_pk_bf16_f32 v175, v176, v177
	s_waitcnt lgkmcnt(3)
	v_mfma_f32_16x16x32_bf16 v[194:197], v[186:189], v[42:45], v[6:9]
	v_cvt_pk_bf16_f32 v176, v206, v207
	s_nop 1
	v_exp_f32_e32 v190, v190
	v_exp_f32_e32 v191, v191
	v_mfma_f32_16x16x32_bf16 v[182:185], v[182:185], v[46:49], v[14:17]
	s_nop 1
	v_exp_f32_e32 v194, v194
	v_exp_f32_e32 v195, v195
	v_exp_f32_e32 v226, v192
	v_mfma_f32_16x16x32_bf16 v[186:189], v[186:189], v[46:49], v[14:17]
	v_exp_f32_e32 v196, v196
	s_nop 0
	v_exp_f32_e32 v182, v182
	v_exp_f32_e32 v183, v183
	v_mfma_f32_16x16x32_bf16 v[86:89], v[240:243], v[166:169], v[86:89]
	v_exp_f32_e32 v184, v184
	s_nop 1
	v_exp_f32_e32 v186, v186
	v_exp_f32_e32 v187, v187
	v_mfma_f32_16x16x32_bf16 v[78:81], v[170:173], v[166:169], v[78:81]
	v_exp_f32_e32 v188, v188
	v_exp_f32_e32 v185, v185
	v_exp_f32_e32 v189, v189
	s_waitcnt lgkmcnt(1)
	v_mfma_f32_16x16x32_bf16 v[74:77], v[210:213], v[166:169], v[74:77]
	v_cvt_pk_bf16_f32 v177, v208, v209
	v_cvt_pk_bf16_f32 v182, v182, v183
	v_cvt_pk_bf16_f32 v183, v184, v185
	v_mfma_f32_16x16x32_bf16 v[70:73], v[214:217], v[166:169], v[70:73]
	v_cvt_pk_bf16_f32 v184, v186, v187
	v_cvt_pk_bf16_f32 v185, v188, v189
	v_mfma_f32_16x16x32_bf16 v[62:65], v[218:221], v[166:169], v[62:65]
	v_exp_f32_e32 v167, v193
	v_exp_f32_e32 v169, v197
	v_cvt_pk_bf16_f32 v166, v190, v191
	s_waitcnt lgkmcnt(0)
	v_mfma_f32_16x16x32_bf16 v[178:181], v[198:201], v[34:37], v[2:5]
	v_cvt_pk_bf16_f32 v167, v226, v167
	v_cvt_pk_bf16_f32 v168, v194, v195
	v_cvt_pk_bf16_f32 v169, v196, v169
	v_mfma_f32_16x16x32_bf16 v[206:209], v[202:205], v[34:37], v[2:5]
	v_mfma_f32_16x16x32_bf16 v[198:201], v[198:201], v[38:41], v[10:13]
	s_nop 2
	v_exp_f32_e32 v178, v178
	s_nop 2
	v_exp_f32_e32 v186, v206
	v_mfma_f32_16x16x32_bf16 v[202:205], v[202:205], v[38:41], v[10:13]
	v_mfma_f32_16x16x32_bf16 v[122:125], v[170:173], v[174:177], v[122:125]
	v_exp_f32_e32 v188, v200
	s_nop 5
	v_exp_f32_e32 v187, v203
	v_exp_f32_e32 v189, v205
	v_mfma_f32_16x16x32_bf16 v[102:105], v[170:173], v[166:169], v[102:105]
	v_mfma_f32_16x16x32_bf16 v[58:61], v[170:173], v[182:185], v[58:61]
	v_exp_f32_e32 v170, v179
	v_exp_f32_e32 v172, v207
	v_exp_f32_e32 v171, v180
	v_exp_f32_e32 v179, v181
	v_mfma_f32_16x16x32_bf16 v[126:129], v[240:243], v[174:177], v[126:129]
	v_exp_f32_e32 v173, v208
	v_exp_f32_e32 v180, v209
	v_cvt_pk_bf16_f32 v170, v178, v170
	v_mfma_f32_16x16x32_bf16 v[118:121], v[210:213], v[174:177], v[118:121]
	v_cvt_pk_bf16_f32 v171, v171, v179
	v_cvt_pk_bf16_f32 v172, v186, v172
	v_exp_f32_e32 v178, v198
	v_mfma_f32_16x16x32_bf16 v[110:113], v[214:217], v[174:177], v[110:113]
	v_exp_f32_e32 v186, v202
	v_exp_f32_e32 v179, v199
	v_cvt_pk_bf16_f32 v173, v173, v180
	v_mfma_f32_16x16x32_bf16 v[106:109], v[218:221], v[174:177], v[106:109]
	ds_read_b128 v[174:177], v247 offset:14336
	v_mfma_f32_16x16x32_bf16 v[114:117], v[240:243], v[166:169], v[114:117]
	v_mfma_f32_16x16x32_bf16 v[98:101], v[210:213], v[166:169], v[98:101]
	v_mfma_f32_16x16x32_bf16 v[94:97], v[214:217], v[166:169], v[94:97]
	v_mfma_f32_16x16x32_bf16 v[90:93], v[218:221], v[166:169], v[90:93]
	v_exp_f32_e32 v169, v204
	v_exp_f32_e32 v167, v201
	v_mfma_f32_16x16x32_bf16 v[82:85], v[240:243], v[182:185], v[82:85]
	v_cvt_pk_bf16_f32 v166, v178, v179
	ds_read_b64 v[178:179], v248 offset:42048
	ds_read_b64 v[180:181], v248 offset:42080
	v_cvt_pk_bf16_f32 v168, v186, v187
	v_mfma_f32_16x16x32_bf16 v[54:57], v[210:213], v[182:185], v[54:57]
	v_cvt_pk_bf16_f32 v167, v188, v167
	v_cvt_pk_bf16_f32 v169, v169, v189
	v_mfma_f32_16x16x32_bf16 v[50:53], v[214:217], v[182:185], v[50:53]
	ds_read_b64 v[186:187], v248 offset:46656
	ds_read_b64 v[188:189], v248 offset:46688
	ds_read_b64 v[198:199], v248 offset:48960
	ds_read_b64 v[200:201], v248 offset:48992
	v_mfma_f32_16x16x32_bf16 v[66:69], v[218:221], v[182:185], v[66:69]
	ds_read_b64 v[182:183], v248 offset:44352
	ds_read_b64 v[184:185], v248 offset:44384
	v_mfma_f32_16x16x32_bf16 v[190:193], v[222:225], v[42:45], v[6:9]
	s_waitcnt lgkmcnt(8)
	v_mfma_f32_16x16x32_bf16 v[194:197], v[174:177], v[42:45], v[6:9]
	v_mfma_f32_16x16x32_bf16 v[222:225], v[222:225], v[46:49], v[14:17]
	s_nop 4
	v_exp_f32_e32 v190, v190
	s_nop 0
	v_exp_f32_e32 v194, v194
	v_exp_f32_e32 v191, v191
	v_mfma_f32_16x16x32_bf16 v[174:177], v[174:177], v[46:49], v[14:17]
	v_exp_f32_e32 v195, v195
	v_exp_f32_e32 v192, v192
	v_exp_f32_e32 v193, v193
	v_mfma_f32_16x16x32_bf16 v[126:129], v[240:243], v[170:173], v[126:129]
	v_exp_f32_e32 v196, v196
	v_exp_f32_e32 v197, v197
	v_cvt_pk_bf16_f32 v190, v190, v191
	v_mfma_f32_16x16x32_bf16 v[86:89], v[240:243], v[166:169], v[86:89]
	v_cvt_pk_bf16_f32 v191, v192, v193
	v_cvt_pk_bf16_f32 v192, v194, v195
	v_exp_f32_e32 v194, v222
	s_waitcnt lgkmcnt(6)
	v_mfma_f32_16x16x32_bf16 v[122:125], v[178:181], v[170:173], v[122:125]
	v_exp_f32_e32 v174, v174
	v_exp_f32_e32 v195, v223
	v_cvt_pk_bf16_f32 v193, v196, v197
	v_mfma_f32_16x16x32_bf16 v[78:81], v[178:181], v[166:169], v[78:81]
	s_waitcnt lgkmcnt(0)
	v_mfma_f32_16x16x32_bf16 v[118:121], v[182:185], v[170:173], v[118:121]
	v_mfma_f32_16x16x32_bf16 v[74:77], v[182:185], v[166:169], v[74:77]
	v_mfma_f32_16x16x32_bf16 v[110:113], v[186:189], v[170:173], v[110:113]
	v_mfma_f32_16x16x32_bf16 v[70:73], v[186:189], v[166:169], v[70:73]
	v_mfma_f32_16x16x32_bf16 v[106:109], v[198:201], v[170:173], v[106:109]
	v_exp_f32_e32 v170, v175
	v_exp_f32_e32 v171, v224
	v_exp_f32_e32 v172, v176
	v_mfma_f32_16x16x32_bf16 v[62:65], v[198:201], v[166:169], v[62:65]
	v_exp_f32_e32 v167, v225
	v_exp_f32_e32 v169, v177
	v_cvt_pk_bf16_f32 v166, v194, v195
	v_cvt_pk_bf16_f32 v168, v174, v170
	v_cvt_pk_bf16_f32 v167, v171, v167
	v_cvt_pk_bf16_f32 v169, v172, v169
	v_mfma_f32_16x16x32_bf16 v[114:117], v[240:243], v[190:193], v[114:117]
	s_nop 0
	v_mfma_f32_16x16x32_bf16 v[82:85], v[240:243], v[166:169], v[82:85]
	v_mfma_f32_16x16x32_bf16 v[102:105], v[178:181], v[190:193], v[102:105]
	v_mfma_f32_16x16x32_bf16 v[58:61], v[178:181], v[166:169], v[58:61]
	v_mfma_f32_16x16x32_bf16 v[98:101], v[182:185], v[190:193], v[98:101]
	v_mfma_f32_16x16x32_bf16 v[54:57], v[182:185], v[166:169], v[54:57]
	v_mfma_f32_16x16x32_bf16 v[94:97], v[186:189], v[190:193], v[94:97]
	v_mfma_f32_16x16x32_bf16 v[50:53], v[186:189], v[166:169], v[50:53]
	v_mfma_f32_16x16x32_bf16 v[90:93], v[198:201], v[190:193], v[90:93]
	v_mfma_f32_16x16x32_bf16 v[66:69], v[198:201], v[166:169], v[66:69]
	v_xor_b32_e32 v246, 0x4000, v246
	v_xor_b32_e32 v247, 0x4000, v247
	v_xor_b32_e32 v244, 0x4000, v244
	v_add_u32_e32 v248, s99, v248
	v_add_u32_e32 v245, s99, v245
	s_sub_i32 s99, 0, s99
	s_cbranch_vccnz .LBB0_2162
.LBB0_2160:
	s_and_b32 s0, s10, 0x80
	s_lshl_b32 s1, s0, 7
	s_add_i32 s37, s1, 0
	s_lshl_b32 s0, s0, 4
	s_add_i32 s2, s37, s0
	s_cmpk_gt_u32 s36, 0x101
	s_cselect_b64 s[0:1], -1, 0
	s_and_b64 vcc, exec, s[0:1]
	s_waitcnt vmcnt(3)
	ds_write_b128 v244, v[18:21]
	s_waitcnt vmcnt(1)
	ds_write_b128 v245, v[22:25] offset:32768
	s_waitcnt vmcnt(1)
	ds_write_b128 v244, v[26:29] offset:8192
	s_waitcnt vmcnt(0)
	ds_write_b128 v245, v[30:33] offset:41984
	s_waitcnt lgkmcnt(0)
	s_barrier
	s_cbranch_vccnz .LBB0_2159
	s_add_i32 s38, s33, s10
	s_add_i32 s39, s38, 0xffffff80
	s_sub_i32 s40, s38, 64
	s_cmp_eq_u32 s10, 0
	s_cselect_b32 s38, s34, s39
	v_add_u32_e32 v18, s38, v159
	v_mad_i64_i32 v[18:19], s[38:39], v18, s19, v[144:145]
	s_cselect_b32 s38, s35, s40
	s_nop 0
	v_add_u32_e32 v20, s38, v159
	v_mad_i64_i32 v[22:23], s[38:39], v20, s19, v[144:145]
	global_load_dwordx4 v[18:21], v[18:19], off offset:3648
	s_nop 0
	global_load_dwordx4 v[26:29], v[22:23], off offset:3648
	s_nop 0
	global_load_dwordx4 v[22:25], v[146:147], off
	global_load_dwordx4 v[30:33], v[146:147], off offset:128
	s_branch .LBB0_2159

.LBB0_2236:
	s_add_i32 s3, s3, s22
	s_cmpk_lt_i32 s3, 0x820
	s_branch .LBB0_2242
.LBB0_2237:
	s_ashr_i32 s0, s3, 2
	s_mul_hi_i32 s1, s0, 0x7e07e07f
	s_lshr_b32 s2, s1, 31
	s_ashr_i32 s1, s1, 7
	s_add_i32 s2, s1, s2
	s_mul_i32 s1, s2, 0x104
	s_sub_i32 s35, s0, s1
	s_cmp_lt_i32 s35, 4
	s_cbranch_scc0 .Lg3l1_go
	s_movk_i32 s0, 0x400
	s_cmp_lt_i32 s3, 16
	s_cselect_b32 s0, 0x800, s0
	s_add_i32 s3, s3, s0
	s_branch .LBB0_2237
.Lg3l1_go:
	v_mov_b32_e32 v2, v141
	s_cmp_gt_i32 s35, 3
	s_mov_b64 s[0:1], -1
	s_cbranch_scc0 .LBB0_2240
	s_lshl_b32 s0, s2, 14
	s_lshl_b32 s1, s35, 6
	s_add_i32 s0, s0, s1
	s_add_i32 s33, s0, 0xffffff00
	s_mov_b64 s[0:1], 0

	.amdhsa_kernel _Z8mega_fwd4Args
		.amdhsa_group_segment_fixed_size 0
		.amdhsa_private_segment_fixed_size 0
		.amdhsa_kernarg_size 544
		.amdhsa_user_sgpr_count 2
		.amdhsa_user_sgpr_dispatch_ptr 0
		.amdhsa_user_sgpr_queue_ptr 0
		.amdhsa_user_sgpr_kernarg_segment_ptr 1
		.amdhsa_user_sgpr_dispatch_id 0
		.amdhsa_user_sgpr_kernarg_preload_length 0
		.amdhsa_user_sgpr_kernarg_preload_offset 0
		.amdhsa_user_sgpr_private_segment_size 0
		.amdhsa_uses_dynamic_stack 0
		.amdhsa_enable_private_segment 0
		.amdhsa_system_sgpr_workgroup_id_x 1
		.amdhsa_system_sgpr_workgroup_id_y 0
		.amdhsa_system_sgpr_workgroup_id_z 0
		.amdhsa_system_sgpr_workgroup_info 0
		.amdhsa_system_vgpr_workitem_id 2
		.amdhsa_next_free_vgpr 256
		.amdhsa_next_free_sgpr 100
		.amdhsa_accum_offset 256
		.amdhsa_reserve_vcc 1
		.amdhsa_float_round_mode_32 0
		.amdhsa_float_round_mode_16_64 0
		.amdhsa_float_denorm_mode_32 3
		.amdhsa_float_denorm_mode_16_64 3
		.amdhsa_dx10_clamp 1
		.amdhsa_ieee_mode 1
		.amdhsa_fp16_overflow 0
		.amdhsa_tg_split 0
		.amdhsa_exception_fp_ieee_invalid_op 0
		.amdhsa_exception_fp_denorm_src 0
		.amdhsa_exception_fp_ieee_div_zero 0
		.amdhsa_exception_fp_ieee_overflow 0
		.amdhsa_exception_fp_ieee_underflow 0
		.amdhsa_exception_fp_ieee_inexact 0
		.amdhsa_exception_int_div_zero 0
	.end_amdhsa_kernel

amdhsa.kernels:
  - .agpr_count:     0
    .args:
      - .offset:         0
        .size:           288
        .value_kind:     by_value
      - .offset:         288
        .size:           4
        .value_kind:     hidden_block_count_x
      - .offset:         292
        .size:           4
        .value_kind:     hidden_block_count_y
      - .offset:         296
        .size:           4
        .value_kind:     hidden_block_count_z
      - .offset:         300
        .size:           2
        .value_kind:     hidden_group_size_x
      - .offset:         302
        .size:           2
        .value_kind:     hidden_group_size_y
      - .offset:         304
        .size:           2
        .value_kind:     hidden_group_size_z
      - .offset:         306
        .size:           2
        .value_kind:     hidden_remainder_x
      - .offset:         308
        .size:           2
        .value_kind:     hidden_remainder_y
      - .offset:         310
        .size:           2
        .value_kind:     hidden_remainder_z
      - .offset:         328
        .size:           8
        .value_kind:     hidden_global_offset_x
      - .offset:         336
        .size:           8
        .value_kind:     hidden_global_offset_y
      - .offset:         344
        .size:           8
        .value_kind:     hidden_global_offset_z
      - .offset:         352
        .size:           2
        .value_kind:     hidden_grid_dims
      - .offset:         376
        .size:           8
        .value_kind:     hidden_multigrid_sync_arg
      - .offset:         408
        .size:           4
        .value_kind:     hidden_dynamic_lds_size
    .group_segment_fixed_size: 0
    .kernarg_segment_align: 8
    .kernarg_segment_size: 544
    .language:       OpenCL C
    .language_version:
      - 2
      - 0
    .max_flat_workgroup_size: 512
    .name:           _Z8mega_fwd4Args
    .private_segment_fixed_size: 0
    .sgpr_count:     106
    .sgpr_spill_count: 96
    .symbol:         _Z8mega_fwd4Args.kd
    .uniform_work_group_size: 1
    .uses_dynamic_stack: false
    .vgpr_count:     256
    .vgpr_spill_count: 0
    .wavefront_size: 64
